# min3 + section 7.4: static s_setprio 1 for waves 4-7 in every GEMM phase, per-segment priority flips deleted
# baseline (speedup 1.0000x reference)
.LBB0_355:
	s_andn2_b64 vcc, exec, s[0:1]
	s_cbranch_vccnz .LBB0_510
	v_lshrrev_b32_e32 v3, 1, v0
	v_and_b32_e32 v146, 24, v3
	v_lshrrev_b32_e32 v3, 5, v0
	s_add_u32 s54, s80, 0xa900000
	s_waitcnt vmcnt(0)
	v_lshlrev_b32_e32 v1, 4, v0
	v_and_b32_e32 v2, 32, v0
	v_and_b32_e32 v3, 4, v3
	v_bfe_u32 v4, v0, 2, 2
	s_addc_u32 s55, s81, 0
	v_bfe_u32 v12, v0, 2, 4
	v_bitop3_b32 v10, v1, v2, 48 bitop3:0x6c
	v_and_b32_e32 v11, 64, v0
	v_or3_b32 v3, v3, v4, v146
	v_lshrrev_b32_e32 v4, 3, v0
	v_or_b32_e32 v13, 0x2000, v1
	s_add_u32 s56, s80, 0x100000
	v_or_b32_e32 v2, v10, v11
	v_and_or_b32 v5, v4, 48, v12
	v_and_or_b32 v4, v4, 32, v3
	v_lshrrev_b32_e32 v1, 7, v13
	s_movk_i32 s0, 0x70
	s_addc_u32 s57, s81, 0
	s_lshr_b32 s1, s2, 6
	v_lshl_or_b32 v150, v4, 11, v2
	v_and_or_b32 v4, v1, s0, v12
	s_movk_i32 s0, 0x60
	s_ashr_i32 s5, s4, 31
	s_ashr_i32 s45, s44, 31
	v_and_or_b32 v1, v1, s0, v3
	s_lshr_b32 s0, s2, 8
	s_lshl_b32 s58, s1, 10
	s_lshl_b64 s[6:7], s[4:5], 19
	s_lshl_b64 s[8:9], s[44:45], 19
	s_add_u32 s8, s56, s8
	s_addc_u32 s9, s57, s9
	s_add_i32 s45, s58, 0
	s_add_i32 m0, s45, 0x10000
	v_lshl_or_b32 v154, v1, 11, v2
	global_load_lds_dwordx4 v150, s[8:9]
	s_add_i32 m0, s45, 0x12000
	s_add_u32 s12, s8, 0x40000
	global_load_lds_dwordx4 v154, s[8:9]
	s_addc_u32 s13, s9, 0
	s_add_i32 m0, s45, 0x14000
	v_lshl_or_b32 v148, v5, 11, v2
	global_load_lds_dwordx4 v150, s[12:13]
	s_add_i32 m0, s45, 0x16000
	s_add_u32 s6, s54, s6
	s_addc_u32 s7, s55, s7
	s_add_i32 s59, s45, 0x2000
	global_load_lds_dwordx4 v154, s[12:13]
	s_mov_b32 m0, s45
	s_add_u32 s12, s6, 0x40000
	v_lshl_or_b32 v152, v4, 11, v2
	global_load_lds_dwordx4 v148, s[6:7]
	s_mov_b32 m0, s59
	s_addc_u32 s13, s7, 0
	s_add_i32 s60, s45, 0x4000
	global_load_lds_dwordx4 v152, s[6:7]
	s_mov_b32 m0, s60
	s_add_i32 s61, s45, 0x6000
	global_load_lds_dwordx4 v148, s[12:13]
	s_mov_b32 m0, s61
	v_mov_b32_e32 v157, 0
	global_load_lds_dwordx4 v152, s[12:13]
	v_mov_b32_e32 v151, v157
	v_mov_b32_e32 v155, v157
	v_mov_b32_e32 v149, v157
	v_mov_b32_e32 v153, v157
	s_cmp_eq_u32 s0, 1
	s_mov_b32 s82, 0
	v_lshl_add_u64 v[8:9], s[8:9], 0, v[150:151]
	v_lshl_add_u64 v[6:7], s[8:9], 0, v[154:155]
	v_lshl_add_u64 v[2:3], s[6:7], 0, v[148:149]
	s_cselect_b64 s[12:13], -1, 0
	s_cmp_lg_u32 s0, 1
	v_lshl_add_u64 v[4:5], s[6:7], 0, v[152:153]
	s_cbranch_scc1 .LBB0_358
	s_setprio 1
	s_barrier

.LBB0_364:
	ds_read_b128 v[130:133], v174
	ds_read_b128 v[134:137], v174 offset:1024
	ds_read_b128 v[138:141], v174 offset:2048
	ds_read_b128 v[142:145], v174 offset:3072
	ds_read_b128 v[166:169], v175
	ds_read_b128 v[182:185], v175 offset:1024
	ds_read_b128 v[186:189], v175 offset:2048
	ds_read_b128 v[190:193], v175 offset:3072
	s_add_u32 s8, s6, 0xfffc0080
	s_addc_u32 s9, s7, -1
	s_cmp_eq_u32 s43, 12
	s_cselect_b32 s51, s2, s9
	s_cselect_b32 s50, s5, s8
	s_cselect_b32 s9, s33, s42
	s_cselect_b32 s8, s35, s37
	v_lshl_add_u64 v[170:171], s[6:7], 0, v[158:159]
	s_add_i32 m0, s45, 0xc000
	ds_read_b128 v[194:197], v178
	ds_read_b128 v[198:201], v178 offset:1024
	ds_read_b128 v[202:205], v178 offset:2048
	ds_read_b128 v[206:209], v178 offset:3072
	ds_read_b128 v[210:213], v178 offset:4096
	ds_read_b128 v[214:217], v178 offset:5120
	ds_read_b128 v[218:221], v178 offset:6144
	ds_read_b128 v[222:225], v178 offset:7168
	global_load_lds_dwordx4 v[170:171], off
	v_lshl_add_u64 v[170:171], s[6:7], 0, v[160:161]
	s_add_i32 m0, s45, 0xe000
	s_nop 0
	global_load_lds_dwordx4 v[170:171], off
	s_waitcnt vmcnt(8)
	s_waitcnt lgkmcnt(0)
	s_barrier
	s_waitcnt lgkmcnt(0)
	v_mfma_f32_16x16x32_bf16 v[126:129], v[130:133], v[194:197], v[126:129]
	v_mfma_f32_16x16x32_bf16 v[122:125], v[138:141], v[194:197], v[122:125]
	v_mfma_f32_16x16x32_bf16 v[110:113], v[130:133], v[202:205], v[110:113]
	v_mfma_f32_16x16x32_bf16 v[106:109], v[138:141], v[202:205], v[106:109]
	v_mfma_f32_16x16x32_bf16 v[94:97], v[130:133], v[210:213], v[94:97]
	v_mfma_f32_16x16x32_bf16 v[90:93], v[138:141], v[210:213], v[90:93]
	v_mfma_f32_16x16x32_bf16 v[78:81], v[130:133], v[218:221], v[78:81]
	v_mfma_f32_16x16x32_bf16 v[74:77], v[138:141], v[218:221], v[74:77]
	v_mfma_f32_16x16x32_bf16 v[126:129], v[134:137], v[198:201], v[126:129]
	v_mfma_f32_16x16x32_bf16 v[122:125], v[142:145], v[198:201], v[122:125]
	v_mfma_f32_16x16x32_bf16 v[110:113], v[134:137], v[206:209], v[110:113]
	v_mfma_f32_16x16x32_bf16 v[106:109], v[142:145], v[206:209], v[106:109]
	v_mfma_f32_16x16x32_bf16 v[94:97], v[134:137], v[214:217], v[94:97]
	v_mfma_f32_16x16x32_bf16 v[90:93], v[142:145], v[214:217], v[90:93]
	v_mfma_f32_16x16x32_bf16 v[78:81], v[134:137], v[222:225], v[78:81]
	v_mfma_f32_16x16x32_bf16 v[74:77], v[142:145], v[222:225], v[74:77]
	v_mfma_f32_16x16x32_bf16 v[118:121], v[166:169], v[194:197], v[118:121]
	v_mfma_f32_16x16x32_bf16 v[114:117], v[186:189], v[194:197], v[114:117]
	v_mfma_f32_16x16x32_bf16 v[102:105], v[166:169], v[202:205], v[102:105]
	v_mfma_f32_16x16x32_bf16 v[98:101], v[186:189], v[202:205], v[98:101]
	v_mfma_f32_16x16x32_bf16 v[86:89], v[166:169], v[210:213], v[86:89]
	v_mfma_f32_16x16x32_bf16 v[82:85], v[186:189], v[210:213], v[82:85]
	v_mfma_f32_16x16x32_bf16 v[70:73], v[166:169], v[218:221], v[70:73]
	v_mfma_f32_16x16x32_bf16 v[66:69], v[186:189], v[218:221], v[66:69]
	v_mfma_f32_16x16x32_bf16 v[118:121], v[182:185], v[198:201], v[118:121]
	v_mfma_f32_16x16x32_bf16 v[114:117], v[190:193], v[198:201], v[114:117]
	v_mfma_f32_16x16x32_bf16 v[102:105], v[182:185], v[206:209], v[102:105]
	v_mfma_f32_16x16x32_bf16 v[98:101], v[190:193], v[206:209], v[98:101]
	v_mfma_f32_16x16x32_bf16 v[86:89], v[182:185], v[214:217], v[86:89]
	v_mfma_f32_16x16x32_bf16 v[82:85], v[190:193], v[214:217], v[82:85]
	v_mfma_f32_16x16x32_bf16 v[70:73], v[182:185], v[222:225], v[70:73]
	v_mfma_f32_16x16x32_bf16 v[66:69], v[190:193], v[222:225], v[66:69]
	s_barrier
	s_add_i32 s46, s90, s58
	v_lshl_add_u64 v[170:171], s[8:9], 0, v[150:151]
	s_mov_b32 m0, s46
	ds_read_b128 v[194:197], v178 offset:16384
	ds_read_b128 v[198:201], v178 offset:17408
	ds_read_b128 v[202:205], v178 offset:18432
	ds_read_b128 v[206:209], v178 offset:19456
	ds_read_b128 v[210:213], v178 offset:20480
	ds_read_b128 v[214:217], v178 offset:21504
	ds_read_b128 v[218:221], v178 offset:22528
	ds_read_b128 v[222:225], v178 offset:23552
	global_load_lds_dwordx4 v[170:171], off
	s_add_i32 m0, s46, 0x2000
	s_add_u32 s46, s8, 0x40000
	v_lshl_add_u64 v[226:227], s[8:9], 0, v[154:155]
	s_addc_u32 s47, s9, 0
	s_add_i32 s52, s91, s58
	global_load_lds_dwordx4 v[226:227], off
	v_lshl_add_u64 v[228:229], s[46:47], 0, v[150:151]
	s_mov_b32 m0, s52
	v_lshl_add_u64 v[230:231], s[50:51], 0, v[152:153]
	global_load_lds_dwordx4 v[228:229], off
	v_lshl_add_u64 v[228:229], s[46:47], 0, v[154:155]
	s_add_i32 m0, s52, 0x2000
	s_nop 0
	global_load_lds_dwordx4 v[228:229], off
	v_lshl_add_u64 v[228:229], s[50:51], 0, v[148:149]
	s_mov_b32 m0, s45
	s_nop 0
	global_load_lds_dwordx4 v[228:229], off
	s_mov_b32 m0, s59
	s_nop 0
	global_load_lds_dwordx4 v[230:231], off
	s_waitcnt vmcnt(8)
	s_waitcnt lgkmcnt(0)
	s_barrier
	s_waitcnt lgkmcnt(0)
	v_mfma_f32_16x16x32_bf16 v[62:65], v[130:133], v[194:197], v[62:65]
	v_mfma_f32_16x16x32_bf16 v[58:61], v[138:141], v[194:197], v[58:61]
	v_mfma_f32_16x16x32_bf16 v[46:49], v[130:133], v[202:205], v[46:49]
	v_mfma_f32_16x16x32_bf16 v[42:45], v[138:141], v[202:205], v[42:45]
	v_mfma_f32_16x16x32_bf16 v[30:33], v[130:133], v[210:213], v[30:33]
	v_mfma_f32_16x16x32_bf16 v[26:29], v[138:141], v[210:213], v[26:29]
	v_mfma_f32_16x16x32_bf16 v[14:17], v[130:133], v[218:221], v[14:17]
	v_mfma_f32_16x16x32_bf16 v[10:13], v[138:141], v[218:221], v[10:13]
	v_mfma_f32_16x16x32_bf16 v[62:65], v[134:137], v[198:201], v[62:65]
	v_mfma_f32_16x16x32_bf16 v[58:61], v[142:145], v[198:201], v[58:61]
	v_mfma_f32_16x16x32_bf16 v[46:49], v[134:137], v[206:209], v[46:49]
	v_mfma_f32_16x16x32_bf16 v[42:45], v[142:145], v[206:209], v[42:45]
	v_mfma_f32_16x16x32_bf16 v[30:33], v[134:137], v[214:217], v[30:33]
	v_mfma_f32_16x16x32_bf16 v[26:29], v[142:145], v[214:217], v[26:29]
	v_mfma_f32_16x16x32_bf16 v[14:17], v[134:137], v[222:225], v[14:17]
	v_mfma_f32_16x16x32_bf16 v[10:13], v[142:145], v[222:225], v[10:13]
	v_mfma_f32_16x16x32_bf16 v[54:57], v[166:169], v[194:197], v[54:57]
	v_mfma_f32_16x16x32_bf16 v[50:53], v[186:189], v[194:197], v[50:53]
	v_mfma_f32_16x16x32_bf16 v[38:41], v[166:169], v[202:205], v[38:41]
	v_mfma_f32_16x16x32_bf16 v[34:37], v[186:189], v[202:205], v[34:37]
	v_mfma_f32_16x16x32_bf16 v[22:25], v[166:169], v[210:213], v[22:25]
	v_mfma_f32_16x16x32_bf16 v[18:21], v[186:189], v[210:213], v[18:21]
	v_mfma_f32_16x16x32_bf16 v[6:9], v[166:169], v[218:221], v[6:9]
	v_mfma_f32_16x16x32_bf16 v[2:5], v[186:189], v[218:221], v[2:5]
	v_mfma_f32_16x16x32_bf16 v[54:57], v[182:185], v[198:201], v[54:57]
	v_mfma_f32_16x16x32_bf16 v[50:53], v[190:193], v[198:201], v[50:53]
	v_mfma_f32_16x16x32_bf16 v[38:41], v[182:185], v[206:209], v[38:41]
	v_mfma_f32_16x16x32_bf16 v[34:37], v[190:193], v[206:209], v[34:37]
	v_mfma_f32_16x16x32_bf16 v[22:25], v[182:185], v[214:217], v[22:25]
	v_mfma_f32_16x16x32_bf16 v[18:21], v[190:193], v[214:217], v[18:21]
	v_mfma_f32_16x16x32_bf16 v[6:9], v[182:185], v[222:225], v[6:9]
	v_mfma_f32_16x16x32_bf16 v[2:5], v[190:193], v[222:225], v[2:5]
	s_barrier
	s_add_i32 s52, 0, 0x18000
	s_add_i32 s53, 0, 0x1c000
	v_add_u32_e32 v142, s52, v147
	v_add_u32_e32 v156, s53, v147
	ds_read_b128 v[130:133], v142
	ds_read_b128 v[134:137], v142 offset:1024
	ds_read_b128 v[138:141], v142 offset:2048
	ds_read_b128 v[142:145], v142 offset:3072
	ds_read_b128 v[166:169], v156
	ds_read_b128 v[182:185], v156 offset:1024
	ds_read_b128 v[186:189], v156 offset:2048
	ds_read_b128 v[190:193], v156 offset:3072
	s_add_u32 s46, s50, 0x40000
	s_addc_u32 s47, s51, 0
	s_mov_b32 m0, s60
	v_lshl_add_u64 v[232:233], s[46:47], 0, v[148:149]
	ds_read_b128 v[194:197], v178 offset:32768
	ds_read_b128 v[198:201], v178 offset:33792
	ds_read_b128 v[202:205], v178 offset:34816
	ds_read_b128 v[206:209], v178 offset:35840
	ds_read_b128 v[210:213], v178 offset:36864
	ds_read_b128 v[214:217], v178 offset:37888
	ds_read_b128 v[218:221], v178 offset:38912
	ds_read_b128 v[222:225], v178 offset:39936
	global_load_lds_dwordx4 v[232:233], off
	v_lshl_add_u64 v[232:233], s[46:47], 0, v[152:153]
	s_mov_b32 m0, s61
	s_nop 0
	global_load_lds_dwordx4 v[232:233], off
	s_waitcnt vmcnt(8)
	s_waitcnt lgkmcnt(0)
	s_barrier
	s_waitcnt lgkmcnt(0)
	v_mfma_f32_16x16x32_bf16 v[126:129], v[130:133], v[194:197], v[126:129]
	v_mfma_f32_16x16x32_bf16 v[122:125], v[138:141], v[194:197], v[122:125]
	v_mfma_f32_16x16x32_bf16 v[110:113], v[130:133], v[202:205], v[110:113]
	v_mfma_f32_16x16x32_bf16 v[106:109], v[138:141], v[202:205], v[106:109]
	v_mfma_f32_16x16x32_bf16 v[94:97], v[130:133], v[210:213], v[94:97]
	v_mfma_f32_16x16x32_bf16 v[90:93], v[138:141], v[210:213], v[90:93]
	v_mfma_f32_16x16x32_bf16 v[78:81], v[130:133], v[218:221], v[78:81]
	v_mfma_f32_16x16x32_bf16 v[74:77], v[138:141], v[218:221], v[74:77]
	v_mfma_f32_16x16x32_bf16 v[126:129], v[134:137], v[198:201], v[126:129]
	v_mfma_f32_16x16x32_bf16 v[122:125], v[142:145], v[198:201], v[122:125]
	v_mfma_f32_16x16x32_bf16 v[110:113], v[134:137], v[206:209], v[110:113]
	v_mfma_f32_16x16x32_bf16 v[106:109], v[142:145], v[206:209], v[106:109]
	v_mfma_f32_16x16x32_bf16 v[94:97], v[134:137], v[214:217], v[94:97]
	v_mfma_f32_16x16x32_bf16 v[90:93], v[142:145], v[214:217], v[90:93]
	v_mfma_f32_16x16x32_bf16 v[78:81], v[134:137], v[222:225], v[78:81]
	v_mfma_f32_16x16x32_bf16 v[74:77], v[142:145], v[222:225], v[74:77]
	v_mfma_f32_16x16x32_bf16 v[118:121], v[166:169], v[194:197], v[118:121]
	v_mfma_f32_16x16x32_bf16 v[114:117], v[186:189], v[194:197], v[114:117]
	v_mfma_f32_16x16x32_bf16 v[102:105], v[166:169], v[202:205], v[102:105]
	v_mfma_f32_16x16x32_bf16 v[98:101], v[186:189], v[202:205], v[98:101]
	v_mfma_f32_16x16x32_bf16 v[86:89], v[166:169], v[210:213], v[86:89]
	v_mfma_f32_16x16x32_bf16 v[82:85], v[186:189], v[210:213], v[82:85]
	v_mfma_f32_16x16x32_bf16 v[70:73], v[166:169], v[218:221], v[70:73]
	v_mfma_f32_16x16x32_bf16 v[66:69], v[186:189], v[218:221], v[66:69]
	v_mfma_f32_16x16x32_bf16 v[118:121], v[182:185], v[198:201], v[118:121]
	v_mfma_f32_16x16x32_bf16 v[114:117], v[190:193], v[198:201], v[114:117]
	v_mfma_f32_16x16x32_bf16 v[102:105], v[182:185], v[206:209], v[102:105]
	v_mfma_f32_16x16x32_bf16 v[98:101], v[190:193], v[206:209], v[98:101]
	v_mfma_f32_16x16x32_bf16 v[86:89], v[182:185], v[214:217], v[86:89]
	v_mfma_f32_16x16x32_bf16 v[82:85], v[190:193], v[214:217], v[82:85]
	v_mfma_f32_16x16x32_bf16 v[70:73], v[182:185], v[222:225], v[70:73]
	v_mfma_f32_16x16x32_bf16 v[66:69], v[190:193], v[222:225], v[66:69]
	s_barrier
	s_add_i32 s46, s52, s58
	v_lshl_add_u64 v[170:171], v[170:171], 0, s[20:21]
	s_mov_b32 m0, s46
	ds_read_b128 v[194:197], v178 offset:49152
	ds_read_b128 v[198:201], v178 offset:50176
	ds_read_b128 v[202:205], v178 offset:51200
	ds_read_b128 v[206:209], v178 offset:52224
	ds_read_b128 v[210:213], v178 offset:53248
	ds_read_b128 v[214:217], v178 offset:54272
	ds_read_b128 v[218:221], v178 offset:55296
	ds_read_b128 v[222:225], v178 offset:56320
	global_load_lds_dwordx4 v[170:171], off
	s_add_i32 m0, s46, 0x2000
	s_add_u32 s8, s8, 0x40080
	v_lshl_add_u64 v[170:171], v[226:227], 0, s[20:21]
	s_addc_u32 s9, s9, 0
	s_add_i32 s46, s53, s58
	global_load_lds_dwordx4 v[170:171], off
	v_lshl_add_u64 v[170:171], s[8:9], 0, v[150:151]
	s_mov_b32 m0, s46
	s_nop 0
	global_load_lds_dwordx4 v[170:171], off
	v_lshl_add_u64 v[170:171], s[8:9], 0, v[154:155]
	s_add_i32 m0, s46, 0x2000
	s_nop 0
	global_load_lds_dwordx4 v[170:171], off
	v_lshl_add_u64 v[170:171], v[228:229], 0, s[20:21]
	s_mov_b32 m0, s80
	s_nop 0
	global_load_lds_dwordx4 v[170:171], off
	v_lshl_add_u64 v[170:171], v[230:231], 0, s[20:21]
	s_mov_b32 m0, s81
	s_nop 0
	global_load_lds_dwordx4 v[170:171], off
	s_waitcnt vmcnt(8)
	s_waitcnt lgkmcnt(0)
	s_barrier
	s_waitcnt lgkmcnt(0)
	v_mfma_f32_16x16x32_bf16 v[62:65], v[130:133], v[194:197], v[62:65]
	v_mfma_f32_16x16x32_bf16 v[58:61], v[138:141], v[194:197], v[58:61]
	v_mfma_f32_16x16x32_bf16 v[46:49], v[130:133], v[202:205], v[46:49]
	v_mfma_f32_16x16x32_bf16 v[42:45], v[138:141], v[202:205], v[42:45]
	v_mfma_f32_16x16x32_bf16 v[30:33], v[130:133], v[210:213], v[30:33]
	v_mfma_f32_16x16x32_bf16 v[26:29], v[138:141], v[210:213], v[26:29]
	v_mfma_f32_16x16x32_bf16 v[14:17], v[130:133], v[218:221], v[14:17]
	v_mfma_f32_16x16x32_bf16 v[10:13], v[138:141], v[218:221], v[10:13]
	v_mfma_f32_16x16x32_bf16 v[62:65], v[134:137], v[198:201], v[62:65]
	v_mfma_f32_16x16x32_bf16 v[58:61], v[142:145], v[198:201], v[58:61]
	v_mfma_f32_16x16x32_bf16 v[46:49], v[134:137], v[206:209], v[46:49]
	v_mfma_f32_16x16x32_bf16 v[42:45], v[142:145], v[206:209], v[42:45]
	v_mfma_f32_16x16x32_bf16 v[30:33], v[134:137], v[214:217], v[30:33]
	v_mfma_f32_16x16x32_bf16 v[26:29], v[142:145], v[214:217], v[26:29]
	v_mfma_f32_16x16x32_bf16 v[14:17], v[134:137], v[222:225], v[14:17]
	v_mfma_f32_16x16x32_bf16 v[10:13], v[142:145], v[222:225], v[10:13]
	v_mfma_f32_16x16x32_bf16 v[54:57], v[166:169], v[194:197], v[54:57]
	v_mfma_f32_16x16x32_bf16 v[50:53], v[186:189], v[194:197], v[50:53]
	v_mfma_f32_16x16x32_bf16 v[38:41], v[166:169], v[202:205], v[38:41]
	v_mfma_f32_16x16x32_bf16 v[34:37], v[186:189], v[202:205], v[34:37]
	v_mfma_f32_16x16x32_bf16 v[22:25], v[166:169], v[210:213], v[22:25]
	v_mfma_f32_16x16x32_bf16 v[18:21], v[186:189], v[210:213], v[18:21]
	v_mfma_f32_16x16x32_bf16 v[6:9], v[166:169], v[218:221], v[6:9]
	v_mfma_f32_16x16x32_bf16 v[2:5], v[186:189], v[218:221], v[2:5]
	v_mfma_f32_16x16x32_bf16 v[54:57], v[182:185], v[198:201], v[54:57]
	v_mfma_f32_16x16x32_bf16 v[50:53], v[190:193], v[198:201], v[50:53]
	v_mfma_f32_16x16x32_bf16 v[38:41], v[182:185], v[206:209], v[38:41]
	v_mfma_f32_16x16x32_bf16 v[34:37], v[190:193], v[206:209], v[34:37]
	v_mfma_f32_16x16x32_bf16 v[22:25], v[182:185], v[214:217], v[22:25]
	v_mfma_f32_16x16x32_bf16 v[18:21], v[190:193], v[214:217], v[18:21]
	v_mfma_f32_16x16x32_bf16 v[6:9], v[182:185], v[222:225], v[6:9]
	v_mfma_f32_16x16x32_bf16 v[2:5], v[190:193], v[222:225], v[2:5]
	s_barrier
	s_add_i32 s43, s43, 2
	s_add_u32 s6, s6, 0x100
	s_addc_u32 s7, s7, 0
	s_add_u32 s37, s37, 0x100
	s_addc_u32 s42, s42, 0
	s_cmp_gt_u32 s43, 13
	s_cbranch_scc0 .LBB0_364
	s_and_b64 vcc, exec, s[22:23]
	s_cbranch_vccz .LBB0_369
	s_barrier
	v_lshl_add_u32 v166, s4, 8, v1
	s_cmp_gt_i32 s44, 3
	s_mov_b64 s[4:5], -1
	s_cbranch_scc1 .LBB0_370

.LBB0_510:
	s_cmp_gt_i32 s83, 2
	s_cselect_b64 s[0:1], -1, 0
	s_and_b64 s[4:5], s[10:11], s[0:1]
	v_readlane_b32 s38, v238, 36
	s_andn2_b64 vcc, exec, s[4:5]
	v_readlane_b32 s39, v238, 37
	s_mov_b32 s40, s92
	s_cbranch_vccnz .LBB0_564
	s_waitcnt vmcnt(0)
	s_waitcnt vmcnt(0)
	s_barrier
	s_setprio 0
	s_and_saveexec_b64 s[4:5], s[38:39]
	s_cbranch_execz .LBB0_563
	s_add_u32 s98, s98, 1
	v_mov_b32_e32 v1, 0x25f20
	ds_read_b64 v[2:3], v1
	v_readlane_b32 s6, v238, 18
	v_readlane_b32 s7, v238, 19
	s_lshl_b32 s2, s87, 8
	s_addk_i32 s2, 0x1400
	v_mov_b32_e32 v1, s2
	v_mov_b32_e32 v5, 1
	s_nop 1
	global_atomic_add v1, v1, v5, s[6:7] sc0
	s_waitcnt vmcnt(0) lgkmcnt(0)
	v_readfirstlane_b32 s12, v1
	v_readfirstlane_b32 s9, v2
	v_readfirstlane_b32 s10, v3
	s_add_u32 s12, s12, 1
	s_mul_i32 s9, s9, s98
	s_mul_i32 s10, s10, s98
	v_mov_b32_e32 v1, 0x3400
	s_cmp_eq_u32 s12, s9
	s_cbranch_scc0 .Lfs0_spin
	buffer_wbl2 sc1
	s_waitcnt vmcnt(0)
	global_atomic_add v1, v5, s[6:7]

.LBB0_855:
	s_cmp_gt_i32 s83, 4
	s_cselect_b64 s[0:1], -1, 0
	s_and_b64 s[4:5], s[6:7], s[0:1]
	s_andn2_b64 vcc, exec, s[4:5]
	s_cbranch_vccnz .LBB0_909
	s_waitcnt vmcnt(0)
	s_waitcnt vmcnt(0) lgkmcnt(0)
	s_barrier
	s_setprio 0
	s_and_saveexec_b64 s[4:5], s[38:39]
	s_cbranch_execz .LBB0_908
	s_add_u32 s98, s98, 1
	v_mov_b32_e32 v1, 0x25f20
	ds_read_b64 v[2:3], v1
	v_readlane_b32 s6, v238, 18
	v_readlane_b32 s7, v238, 19
	s_lshl_b32 s2, s87, 8
	s_addk_i32 s2, 0x1400
	v_mov_b32_e32 v1, s2
	v_mov_b32_e32 v5, 1
	s_nop 1
	global_atomic_add v1, v1, v5, s[6:7] sc0
	s_waitcnt vmcnt(0) lgkmcnt(0)
	v_readfirstlane_b32 s12, v1
	v_readfirstlane_b32 s9, v2
	v_readfirstlane_b32 s10, v3
	s_add_u32 s12, s12, 1
	s_mul_i32 s9, s9, s98
	s_mul_i32 s10, s10, s98
	v_mov_b32_e32 v1, 0x3400
	s_cmp_eq_u32 s12, s9
	s_cbranch_scc0 .Lfs1_spin
	buffer_wbl2 sc1
	s_waitcnt vmcnt(0)
	global_atomic_add v1, v5, s[6:7]

.LBB0_909:
	s_cmp_lt_i32 s82, 5
	s_cselect_b64 s[4:5], -1, 0
	s_and_b64 s[0:1], s[4:5], s[0:1]
	s_andn2_b64 vcc, exec, s[0:1]
	s_cbranch_vccnz .LBB0_938
	s_cmpk_gt_i32 s86, 0x2ff
	v_readfirstlane_b32 s0, v0
	s_cbranch_scc1 .LBB0_938
	s_waitcnt vmcnt(0)
	v_lshrrev_b32_e32 v1, 5, v0
	v_lshrrev_b32_e32 v3, 1, v0
	v_and_b32_e32 v1, 4, v1
	v_bfe_u32 v2, v0, 2, 2
	v_and_b32_e32 v10, 24, v3
	v_or3_b32 v1, v1, v2, v10
	v_lshlrev_b32_e32 v2, 4, v0
	v_bfe_u32 v3, v0, 3, 25
	v_and_b32_e32 v5, 32, v0
	v_or_b32_e32 v3, 64, v3
	s_movk_i32 s4, 0x60
	v_bitop3_b32 v11, v2, v5, 48 bitop3:0x6c
	v_and_b32_e32 v12, 64, v0
	s_add_u32 s27, s80, 0x1bb00000
	v_and_or_b32 v4, v3, s4, v1
	v_or_b32_e32 v2, v11, v12
	s_addc_u32 s44, s81, 0
	v_mul_u32_u24_e32 v4, 0x180, v4
	v_lshrrev_b32_e32 v2, 1, v2
	s_add_u32 s45, s80, 0x2200000
	v_or_b32_e32 v4, v4, v2
	s_addc_u32 s50, s81, 0
	v_lshlrev_b32_e32 v138, 1, v4
	v_bfe_u32 v4, v0, 2, 4
	s_movk_i32 s4, 0x70
	s_ashr_i32 s52, s86, 31
	v_and_or_b32 v3, v3, s4, v4
	s_lshr_b32 s4, s52, 29
	s_add_i32 s4, s86, s4
	s_lshr_b32 s2, s0, 6
	s_ashr_i32 s5, s4, 3
	s_and_b32 s4, s4, -8
	s_lshr_b32 s1, s0, 8
	s_lshl_b32 s51, s2, 10
	s_sub_i32 s4, s86, s4
	s_cmp_lt_i32 s4, 0
	s_movk_i32 s53, 0x61
	s_cselect_b32 s6, s53, 0x60
	s_mul_i32 s4, s6, s4
	s_add_i32 s4, s4, s5
	s_mul_hi_i32 s5, s4, 0x2aaaaaab
	s_lshr_b32 s6, s5, 31
	s_ashr_i32 s5, s5, 3
	s_add_i32 s5, s5, s6
	s_lshl_b32 s6, s5, 3
	s_mul_i32 s5, s5, 48
	s_sub_i32 s5, s4, s5
	s_bfe_i32 s4, s5, 0x80000
	s_bfe_u32 s4, s4, 0x3000c
	s_add_i32 s7, s5, s4
	s_bfe_i32 s4, s7, 0x80000
	s_and_b32 s7, s7, 0xf8
	v_mul_u32_u24_e32 v13, 0x180, v3
	s_sub_i32 s5, s5, s7
	v_or_b32_e32 v3, v13, v2
	s_sext_i32_i16 s8, s4
	s_sext_i32_i8 s5, s5
	v_lshlrev_b32_e32 v140, 1, v3
	v_lshrrev_b32_e32 v3, 3, v0
	s_add_i32 s33, s6, s5
	s_ashr_i32 s6, s8, 3
	v_and_or_b32 v1, v3, 32, v1
	s_lshr_b32 s4, s8, 3
	s_mul_hi_i32 s7, s6, 0x30000
	s_mul_i32 s6, s6, 0x30000
	v_mul_u32_u24_e32 v1, 0x180, v1
	s_add_u32 s38, s45, s6
	v_or_b32_e32 v1, v1, v2
	s_addc_u32 s39, s50, s7
	s_add_i32 s54, s51, 0
	v_lshlrev_b32_e32 v142, 1, v1
	s_add_i32 m0, s54, 0x10000
	v_and_or_b32 v1, v3, 48, v4
	global_load_lds_dwordx4 v142, s[38:39]
	s_add_i32 m0, s54, 0x12000
	s_add_u32 s6, s38, 0x18000
	global_load_lds_dwordx4 v138, s[38:39]
	s_addc_u32 s7, s39, 0
	s_add_i32 m0, s54, 0x14000
	s_mul_i32 s9, s33, 0x30000
	global_load_lds_dwordx4 v142, s[6:7]
	s_add_i32 m0, s54, 0x16000
	v_mul_u32_u24_e32 v14, 0x180, v1
	s_mul_hi_i32 s5, s33, 0x30000
	s_add_u32 s36, s27, s9
	v_or_b32_e32 v1, v2, v14
	s_addc_u32 s37, s44, s5
	s_add_i32 s55, s54, 0x2000
	v_lshlrev_b32_e32 v144, 1, v1
	global_load_lds_dwordx4 v138, s[6:7]
	s_mov_b32 m0, s54
	s_add_u32 s6, s36, 0x18000
	global_load_lds_dwordx4 v144, s[36:37]
	s_mov_b32 m0, s55
	s_addc_u32 s7, s37, 0
	s_add_i32 s56, s54, 0x4000
	global_load_lds_dwordx4 v140, s[36:37]
	s_mov_b32 m0, s56
	s_add_i32 s57, s54, 0x6000
	global_load_lds_dwordx4 v144, s[6:7]
	s_mov_b32 m0, s57
	v_mov_b32_e32 v147, 0
	global_load_lds_dwordx4 v140, s[6:7]
	v_mov_b32_e32 v143, v147
	v_mov_b32_e32 v139, v147
	v_mov_b32_e32 v145, v147
	v_mov_b32_e32 v141, v147
	s_cmp_eq_u32 s1, 1
	s_mov_b32 s88, s40
	s_mov_b32 s58, 0
	v_lshl_add_u64 v[8:9], s[38:39], 0, v[142:143]
	v_lshl_add_u64 v[6:7], s[38:39], 0, v[138:139]
	v_lshl_add_u64 v[2:3], s[36:37], 0, v[144:145]
	s_cselect_b64 s[6:7], -1, 0
	s_cmp_lg_u32 s1, 1
	v_lshl_add_u64 v[4:5], s[36:37], 0, v[140:141]
	s_cbranch_scc1 .LBB0_913
	s_setprio 1
	s_barrier

.LBB0_923:
	ds_read_b128 v[130:133], v183
	ds_read_b128 v[134:137], v183 offset:1024
	ds_read_b128 v[156:159], v183 offset:2048
	ds_read_b128 v[160:163], v183 offset:3072
	ds_read_b128 v[164:167], v184
	ds_read_b128 v[168:171], v184 offset:1024
	ds_read_b128 v[172:175], v184 offset:2048
	ds_read_b128 v[186:189], v184 offset:3072
	s_add_u32 s38, s36, 0xfffe8080
	s_addc_u32 s39, s37, -1
	s_cmp_eq_u32 s46, 2
	s_cselect_b32 s41, s1, s39
	s_cselect_b32 s40, s0, s38
	s_cselect_b32 s39, s35, s43
	s_cselect_b32 s38, s34, s42
	v_lshl_add_u64 v[222:223], s[36:37], 0, v[148:149]
	s_add_i32 m0, s54, 0xc000
	ds_read_b128 v[190:193], v185
	ds_read_b128 v[194:197], v185 offset:1024
	ds_read_b128 v[198:201], v185 offset:2048
	ds_read_b128 v[202:205], v185 offset:3072
	ds_read_b128 v[206:209], v185 offset:4096
	ds_read_b128 v[210:213], v185 offset:5120
	ds_read_b128 v[214:217], v185 offset:6144
	ds_read_b128 v[218:221], v185 offset:7168
	global_load_lds_dwordx4 v[222:223], off
	v_lshl_add_u64 v[222:223], s[36:37], 0, v[150:151]
	s_add_i32 m0, s54, 0xe000
	s_nop 0
	global_load_lds_dwordx4 v[222:223], off
	s_waitcnt vmcnt(8)
	s_waitcnt lgkmcnt(0)
	s_barrier
	s_waitcnt lgkmcnt(0)
	v_mfma_f32_16x16x32_bf16 v[126:129], v[130:133], v[190:193], v[126:129]
	v_mfma_f32_16x16x32_bf16 v[122:125], v[156:159], v[190:193], v[122:125]
	v_mfma_f32_16x16x32_bf16 v[118:121], v[130:133], v[198:201], v[118:121]
	v_mfma_f32_16x16x32_bf16 v[114:117], v[156:159], v[198:201], v[114:117]
	v_mfma_f32_16x16x32_bf16 v[110:113], v[130:133], v[206:209], v[110:113]
	v_mfma_f32_16x16x32_bf16 v[106:109], v[156:159], v[206:209], v[106:109]
	v_mfma_f32_16x16x32_bf16 v[102:105], v[130:133], v[214:217], v[102:105]
	v_mfma_f32_16x16x32_bf16 v[98:101], v[156:159], v[214:217], v[98:101]
	v_mfma_f32_16x16x32_bf16 v[126:129], v[134:137], v[194:197], v[126:129]
	v_mfma_f32_16x16x32_bf16 v[122:125], v[160:163], v[194:197], v[122:125]
	v_mfma_f32_16x16x32_bf16 v[118:121], v[134:137], v[202:205], v[118:121]
	v_mfma_f32_16x16x32_bf16 v[114:117], v[160:163], v[202:205], v[114:117]
	v_mfma_f32_16x16x32_bf16 v[110:113], v[134:137], v[210:213], v[110:113]
	v_mfma_f32_16x16x32_bf16 v[106:109], v[160:163], v[210:213], v[106:109]
	v_mfma_f32_16x16x32_bf16 v[102:105], v[134:137], v[218:221], v[102:105]
	v_mfma_f32_16x16x32_bf16 v[98:101], v[160:163], v[218:221], v[98:101]
	v_mfma_f32_16x16x32_bf16 v[66:69], v[164:167], v[190:193], v[66:69]
	v_mfma_f32_16x16x32_bf16 v[58:61], v[172:175], v[190:193], v[58:61]
	v_mfma_f32_16x16x32_bf16 v[54:57], v[164:167], v[198:201], v[54:57]
	v_mfma_f32_16x16x32_bf16 v[50:53], v[172:175], v[198:201], v[50:53]
	v_mfma_f32_16x16x32_bf16 v[46:49], v[164:167], v[206:209], v[46:49]
	v_mfma_f32_16x16x32_bf16 v[42:45], v[172:175], v[206:209], v[42:45]
	v_mfma_f32_16x16x32_bf16 v[38:41], v[164:167], v[214:217], v[38:41]
	v_mfma_f32_16x16x32_bf16 v[34:37], v[172:175], v[214:217], v[34:37]
	v_mfma_f32_16x16x32_bf16 v[66:69], v[168:171], v[194:197], v[66:69]
	v_mfma_f32_16x16x32_bf16 v[58:61], v[186:189], v[194:197], v[58:61]
	v_mfma_f32_16x16x32_bf16 v[54:57], v[168:171], v[202:205], v[54:57]
	v_mfma_f32_16x16x32_bf16 v[50:53], v[186:189], v[202:205], v[50:53]
	v_mfma_f32_16x16x32_bf16 v[46:49], v[168:171], v[210:213], v[46:49]
	v_mfma_f32_16x16x32_bf16 v[42:45], v[186:189], v[210:213], v[42:45]
	v_mfma_f32_16x16x32_bf16 v[38:41], v[168:171], v[218:221], v[38:41]
	v_mfma_f32_16x16x32_bf16 v[34:37], v[186:189], v[218:221], v[34:37]
	s_barrier
	s_add_i32 s47, s66, s51
	v_lshl_add_u64 v[222:223], s[38:39], 0, v[142:143]
	s_mov_b32 m0, s47
	ds_read_b128 v[190:193], v185 offset:16384
	ds_read_b128 v[194:197], v185 offset:17408
	ds_read_b128 v[198:201], v185 offset:18432
	ds_read_b128 v[202:205], v185 offset:19456
	ds_read_b128 v[206:209], v185 offset:20480
	ds_read_b128 v[210:213], v185 offset:21504
	ds_read_b128 v[214:217], v185 offset:22528
	ds_read_b128 v[218:221], v185 offset:23552
	global_load_lds_dwordx4 v[222:223], off
	s_add_i32 m0, s47, 0x2000
	s_add_u32 s64, s38, 0x18000
	v_lshl_add_u64 v[224:225], s[38:39], 0, v[138:139]
	s_addc_u32 s65, s39, 0
	s_add_i32 s47, s67, s51
	global_load_lds_dwordx4 v[224:225], off
	v_lshl_add_u64 v[226:227], s[64:65], 0, v[142:143]
	s_mov_b32 m0, s47
	v_lshl_add_u64 v[228:229], s[40:41], 0, v[140:141]
	global_load_lds_dwordx4 v[226:227], off
	v_lshl_add_u64 v[226:227], s[64:65], 0, v[138:139]
	s_add_i32 m0, s47, 0x2000
	s_nop 0
	global_load_lds_dwordx4 v[226:227], off
	v_lshl_add_u64 v[226:227], s[40:41], 0, v[144:145]
	s_mov_b32 m0, s54
	s_nop 0
	global_load_lds_dwordx4 v[226:227], off
	s_mov_b32 m0, s55
	s_nop 0
	global_load_lds_dwordx4 v[228:229], off
	s_waitcnt vmcnt(8)
	s_waitcnt lgkmcnt(0)
	s_barrier
	s_waitcnt lgkmcnt(0)
	v_mfma_f32_16x16x32_bf16 v[94:97], v[130:133], v[190:193], v[94:97]
	v_mfma_f32_16x16x32_bf16 v[90:93], v[156:159], v[190:193], v[90:93]
	v_mfma_f32_16x16x32_bf16 v[86:89], v[130:133], v[198:201], v[86:89]
	v_mfma_f32_16x16x32_bf16 v[82:85], v[156:159], v[198:201], v[82:85]
	v_mfma_f32_16x16x32_bf16 v[78:81], v[130:133], v[206:209], v[78:81]
	v_mfma_f32_16x16x32_bf16 v[74:77], v[156:159], v[206:209], v[74:77]
	v_mfma_f32_16x16x32_bf16 v[70:73], v[130:133], v[214:217], v[70:73]
	v_mfma_f32_16x16x32_bf16 v[62:65], v[156:159], v[214:217], v[62:65]
	v_mfma_f32_16x16x32_bf16 v[94:97], v[134:137], v[194:197], v[94:97]
	v_mfma_f32_16x16x32_bf16 v[90:93], v[160:163], v[194:197], v[90:93]
	v_mfma_f32_16x16x32_bf16 v[86:89], v[134:137], v[202:205], v[86:89]
	v_mfma_f32_16x16x32_bf16 v[82:85], v[160:163], v[202:205], v[82:85]
	v_mfma_f32_16x16x32_bf16 v[78:81], v[134:137], v[210:213], v[78:81]
	v_mfma_f32_16x16x32_bf16 v[74:77], v[160:163], v[210:213], v[74:77]
	v_mfma_f32_16x16x32_bf16 v[70:73], v[134:137], v[218:221], v[70:73]
	v_mfma_f32_16x16x32_bf16 v[62:65], v[160:163], v[218:221], v[62:65]
	v_mfma_f32_16x16x32_bf16 v[30:33], v[164:167], v[190:193], v[30:33]
	v_mfma_f32_16x16x32_bf16 v[26:29], v[172:175], v[190:193], v[26:29]
	v_mfma_f32_16x16x32_bf16 v[22:25], v[164:167], v[198:201], v[22:25]
	v_mfma_f32_16x16x32_bf16 v[18:21], v[172:175], v[198:201], v[18:21]
	v_mfma_f32_16x16x32_bf16 v[14:17], v[164:167], v[206:209], v[14:17]
	v_mfma_f32_16x16x32_bf16 v[10:13], v[172:175], v[206:209], v[10:13]
	v_mfma_f32_16x16x32_bf16 v[6:9], v[164:167], v[214:217], v[6:9]
	v_mfma_f32_16x16x32_bf16 v[2:5], v[172:175], v[214:217], v[2:5]
	v_mfma_f32_16x16x32_bf16 v[30:33], v[168:171], v[194:197], v[30:33]
	v_mfma_f32_16x16x32_bf16 v[26:29], v[186:189], v[194:197], v[26:29]
	v_mfma_f32_16x16x32_bf16 v[22:25], v[168:171], v[202:205], v[22:25]
	v_mfma_f32_16x16x32_bf16 v[18:21], v[186:189], v[202:205], v[18:21]
	v_mfma_f32_16x16x32_bf16 v[14:17], v[168:171], v[210:213], v[14:17]
	v_mfma_f32_16x16x32_bf16 v[10:13], v[186:189], v[210:213], v[10:13]
	v_mfma_f32_16x16x32_bf16 v[6:9], v[168:171], v[218:221], v[6:9]
	v_mfma_f32_16x16x32_bf16 v[2:5], v[186:189], v[218:221], v[2:5]
	s_barrier
	s_add_i32 s47, 0, 0x18000
	v_add_u32_e32 v146, s47, v181
	s_add_i32 s64, 0, 0x1c000
	ds_read_b128 v[130:133], v146
	ds_read_b128 v[134:137], v146 offset:1024
	ds_read_b128 v[156:159], v146 offset:2048
	ds_read_b128 v[160:163], v146 offset:3072
	v_add_u32_e32 v146, s64, v181
	ds_read_b128 v[164:167], v146
	ds_read_b128 v[168:171], v146 offset:1024
	ds_read_b128 v[172:175], v146 offset:2048
	ds_read_b128 v[186:189], v146 offset:3072
	s_add_u32 s40, s40, 0x18000
	s_addc_u32 s41, s41, 0
	s_mov_b32 m0, s56
	v_lshl_add_u64 v[230:231], s[40:41], 0, v[144:145]
	ds_read_b128 v[190:193], v185 offset:32768
	ds_read_b128 v[194:197], v185 offset:33792
	ds_read_b128 v[198:201], v185 offset:34816
	ds_read_b128 v[202:205], v185 offset:35840
	ds_read_b128 v[206:209], v185 offset:36864
	ds_read_b128 v[210:213], v185 offset:37888
	ds_read_b128 v[214:217], v185 offset:38912
	ds_read_b128 v[218:221], v185 offset:39936
	global_load_lds_dwordx4 v[230:231], off
	v_lshl_add_u64 v[230:231], s[40:41], 0, v[140:141]
	s_mov_b32 m0, s57
	s_nop 0
	global_load_lds_dwordx4 v[230:231], off
	s_waitcnt vmcnt(8)
	s_waitcnt lgkmcnt(0)
	s_barrier
	s_waitcnt lgkmcnt(0)
	v_mfma_f32_16x16x32_bf16 v[126:129], v[130:133], v[190:193], v[126:129]
	v_mfma_f32_16x16x32_bf16 v[122:125], v[156:159], v[190:193], v[122:125]
	v_mfma_f32_16x16x32_bf16 v[118:121], v[130:133], v[198:201], v[118:121]
	v_mfma_f32_16x16x32_bf16 v[114:117], v[156:159], v[198:201], v[114:117]
	v_mfma_f32_16x16x32_bf16 v[110:113], v[130:133], v[206:209], v[110:113]
	v_mfma_f32_16x16x32_bf16 v[106:109], v[156:159], v[206:209], v[106:109]
	v_mfma_f32_16x16x32_bf16 v[102:105], v[130:133], v[214:217], v[102:105]
	v_mfma_f32_16x16x32_bf16 v[98:101], v[156:159], v[214:217], v[98:101]
	v_mfma_f32_16x16x32_bf16 v[126:129], v[134:137], v[194:197], v[126:129]
	v_mfma_f32_16x16x32_bf16 v[122:125], v[160:163], v[194:197], v[122:125]
	v_mfma_f32_16x16x32_bf16 v[118:121], v[134:137], v[202:205], v[118:121]
	v_mfma_f32_16x16x32_bf16 v[114:117], v[160:163], v[202:205], v[114:117]
	v_mfma_f32_16x16x32_bf16 v[110:113], v[134:137], v[210:213], v[110:113]
	v_mfma_f32_16x16x32_bf16 v[106:109], v[160:163], v[210:213], v[106:109]
	v_mfma_f32_16x16x32_bf16 v[102:105], v[134:137], v[218:221], v[102:105]
	v_mfma_f32_16x16x32_bf16 v[98:101], v[160:163], v[218:221], v[98:101]
	v_mfma_f32_16x16x32_bf16 v[66:69], v[164:167], v[190:193], v[66:69]
	v_mfma_f32_16x16x32_bf16 v[58:61], v[172:175], v[190:193], v[58:61]
	v_mfma_f32_16x16x32_bf16 v[54:57], v[164:167], v[198:201], v[54:57]
	v_mfma_f32_16x16x32_bf16 v[50:53], v[172:175], v[198:201], v[50:53]
	v_mfma_f32_16x16x32_bf16 v[46:49], v[164:167], v[206:209], v[46:49]
	v_mfma_f32_16x16x32_bf16 v[42:45], v[172:175], v[206:209], v[42:45]
	v_mfma_f32_16x16x32_bf16 v[38:41], v[164:167], v[214:217], v[38:41]
	v_mfma_f32_16x16x32_bf16 v[34:37], v[172:175], v[214:217], v[34:37]
	v_mfma_f32_16x16x32_bf16 v[66:69], v[168:171], v[194:197], v[66:69]
	v_mfma_f32_16x16x32_bf16 v[58:61], v[186:189], v[194:197], v[58:61]
	v_mfma_f32_16x16x32_bf16 v[54:57], v[168:171], v[202:205], v[54:57]
	v_mfma_f32_16x16x32_bf16 v[50:53], v[186:189], v[202:205], v[50:53]
	v_mfma_f32_16x16x32_bf16 v[46:49], v[168:171], v[210:213], v[46:49]
	v_mfma_f32_16x16x32_bf16 v[42:45], v[186:189], v[210:213], v[42:45]
	v_mfma_f32_16x16x32_bf16 v[38:41], v[168:171], v[218:221], v[38:41]
	v_mfma_f32_16x16x32_bf16 v[34:37], v[186:189], v[218:221], v[34:37]
	s_barrier
	s_add_i32 s40, s47, s51
	v_lshl_add_u64 v[222:223], v[222:223], 0, s[14:15]
	s_mov_b32 m0, s40
	ds_read_b128 v[190:193], v185 offset:49152
	ds_read_b128 v[194:197], v185 offset:50176
	ds_read_b128 v[198:201], v185 offset:51200
	ds_read_b128 v[202:205], v185 offset:52224
	ds_read_b128 v[206:209], v185 offset:53248
	ds_read_b128 v[210:213], v185 offset:54272
	ds_read_b128 v[214:217], v185 offset:55296
	ds_read_b128 v[218:221], v185 offset:56320
	global_load_lds_dwordx4 v[222:223], off
	s_add_i32 m0, s40, 0x2000
	s_add_u32 s38, s38, 0x18080
	v_lshl_add_u64 v[222:223], v[224:225], 0, s[14:15]
	s_addc_u32 s39, s39, 0
	s_add_i32 s40, s64, s51
	global_load_lds_dwordx4 v[222:223], off
	v_lshl_add_u64 v[222:223], s[38:39], 0, v[142:143]
	s_mov_b32 m0, s40
	s_nop 0
	global_load_lds_dwordx4 v[222:223], off
	v_lshl_add_u64 v[222:223], s[38:39], 0, v[138:139]
	s_add_i32 m0, s40, 0x2000
	s_nop 0
	global_load_lds_dwordx4 v[222:223], off
	v_lshl_add_u64 v[222:223], v[226:227], 0, s[14:15]
	s_mov_b32 m0, s59
	s_nop 0
	global_load_lds_dwordx4 v[222:223], off
	v_lshl_add_u64 v[222:223], v[228:229], 0, s[14:15]
	s_mov_b32 m0, s60
	s_nop 0
	global_load_lds_dwordx4 v[222:223], off
	s_waitcnt vmcnt(8)
	s_waitcnt lgkmcnt(0)
	s_barrier
	s_waitcnt lgkmcnt(0)
	v_mfma_f32_16x16x32_bf16 v[94:97], v[130:133], v[190:193], v[94:97]
	v_mfma_f32_16x16x32_bf16 v[90:93], v[156:159], v[190:193], v[90:93]
	v_mfma_f32_16x16x32_bf16 v[86:89], v[130:133], v[198:201], v[86:89]
	v_mfma_f32_16x16x32_bf16 v[82:85], v[156:159], v[198:201], v[82:85]
	v_mfma_f32_16x16x32_bf16 v[78:81], v[130:133], v[206:209], v[78:81]
	v_mfma_f32_16x16x32_bf16 v[74:77], v[156:159], v[206:209], v[74:77]
	v_mfma_f32_16x16x32_bf16 v[70:73], v[130:133], v[214:217], v[70:73]
	v_mfma_f32_16x16x32_bf16 v[62:65], v[156:159], v[214:217], v[62:65]
	v_mfma_f32_16x16x32_bf16 v[94:97], v[134:137], v[194:197], v[94:97]
	v_mfma_f32_16x16x32_bf16 v[90:93], v[160:163], v[194:197], v[90:93]
	v_mfma_f32_16x16x32_bf16 v[86:89], v[134:137], v[202:205], v[86:89]
	v_mfma_f32_16x16x32_bf16 v[82:85], v[160:163], v[202:205], v[82:85]
	v_mfma_f32_16x16x32_bf16 v[78:81], v[134:137], v[210:213], v[78:81]
	v_mfma_f32_16x16x32_bf16 v[74:77], v[160:163], v[210:213], v[74:77]
	v_mfma_f32_16x16x32_bf16 v[70:73], v[134:137], v[218:221], v[70:73]
	v_mfma_f32_16x16x32_bf16 v[62:65], v[160:163], v[218:221], v[62:65]
	v_mfma_f32_16x16x32_bf16 v[30:33], v[164:167], v[190:193], v[30:33]
	v_mfma_f32_16x16x32_bf16 v[26:29], v[172:175], v[190:193], v[26:29]
	v_mfma_f32_16x16x32_bf16 v[22:25], v[164:167], v[198:201], v[22:25]
	v_mfma_f32_16x16x32_bf16 v[18:21], v[172:175], v[198:201], v[18:21]
	v_mfma_f32_16x16x32_bf16 v[14:17], v[164:167], v[206:209], v[14:17]
	v_mfma_f32_16x16x32_bf16 v[10:13], v[172:175], v[206:209], v[10:13]
	v_mfma_f32_16x16x32_bf16 v[6:9], v[164:167], v[214:217], v[6:9]
	v_mfma_f32_16x16x32_bf16 v[2:5], v[172:175], v[214:217], v[2:5]
	v_mfma_f32_16x16x32_bf16 v[30:33], v[168:171], v[194:197], v[30:33]
	v_mfma_f32_16x16x32_bf16 v[26:29], v[186:189], v[194:197], v[26:29]
	v_mfma_f32_16x16x32_bf16 v[22:25], v[168:171], v[202:205], v[22:25]
	v_mfma_f32_16x16x32_bf16 v[18:21], v[186:189], v[202:205], v[18:21]
	v_mfma_f32_16x16x32_bf16 v[14:17], v[168:171], v[210:213], v[14:17]
	v_mfma_f32_16x16x32_bf16 v[10:13], v[186:189], v[210:213], v[10:13]
	v_mfma_f32_16x16x32_bf16 v[6:9], v[168:171], v[218:221], v[6:9]
	v_mfma_f32_16x16x32_bf16 v[2:5], v[186:189], v[218:221], v[2:5]
	s_barrier
	s_add_i32 s46, s46, 2
	s_add_u32 s36, s36, 0x100
	s_addc_u32 s37, s37, 0
	s_add_u32 s42, s42, 0x100
	s_addc_u32 s43, s43, 0
	s_cmp_gt_u32 s46, 3
	s_cbranch_scc0 .LBB0_923
	s_and_b64 vcc, exec, s[16:17]
	s_cbranch_vccz .LBB0_928
	s_barrier
	s_mov_b64 s[36:37], -1
	s_cmp_gt_u32 s2, 1
	v_lshl_add_u32 v156, s33, 8, v1
	s_cbranch_scc1 .LBB0_929

.LBB0_959:
	s_cmp_gt_i32 s83, 7
	s_cselect_b64 s[4:5], -1, 0
	s_and_b64 s[0:1], s[0:1], s[4:5]
	s_andn2_b64 vcc, exec, s[0:1]
	s_cbranch_vccnz .LBB0_1013
	s_waitcnt vmcnt(0)
	s_waitcnt vmcnt(0) lgkmcnt(0)
	s_barrier
	s_setprio 0
	s_and_saveexec_b64 s[0:1], s[38:39]
	s_cbranch_execz .LBB0_1012
	s_add_u32 s98, s98, 1
	v_mov_b32_e32 v1, 0x25f20
	ds_read_b64 v[2:3], v1
	v_readlane_b32 s6, v238, 18
	v_readlane_b32 s7, v238, 19
	s_lshl_b32 s2, s87, 8
	s_addk_i32 s2, 0x1400
	v_mov_b32_e32 v1, s2
	v_mov_b32_e32 v5, 1
	s_nop 1
	global_atomic_add v1, v1, v5, s[6:7] sc0
	s_waitcnt vmcnt(0) lgkmcnt(0)
	v_readfirstlane_b32 s12, v1
	v_readfirstlane_b32 s9, v2
	v_readfirstlane_b32 s10, v3
	s_add_u32 s12, s12, 1
	s_mul_i32 s9, s9, s98
	s_mul_i32 s10, s10, s98
	v_mov_b32_e32 v1, 0x3400
	s_cmp_eq_u32 s12, s9
	s_cbranch_scc0 .Lfs2_spin
	buffer_wbl2 sc1
	s_waitcnt vmcnt(0)
	global_atomic_add v1, v5, s[6:7]

.LBB0_1147:
	s_barrier
	s_waitcnt vmcnt(0)
	v_readlane_b32 s38, v238, 36
	v_readlane_b32 s39, v238, 37
	s_barrier
	s_setprio 0
	s_and_saveexec_b64 s[0:1], s[38:39]
	v_readlane_b32 s86, v238, 47
	v_readlane_b32 s87, v238, 46
	v_readlane_b32 s40, v238, 58
	v_readlane_b32 s93, v238, 48
	v_readlane_b32 s24, v238, 38
	v_readlane_b32 s41, v238, 59
	s_cbranch_execz .LBB0_1199
	s_add_u32 s98, s98, 1
	v_mov_b32_e32 v1, 0x25f20
	ds_read_b64 v[2:3], v1
	v_readlane_b32 s6, v238, 18
	v_readlane_b32 s7, v238, 19
	s_lshl_b32 s2, s87, 8
	s_addk_i32 s2, 0x1400
	v_mov_b32_e32 v1, s2
	v_mov_b32_e32 v5, 1
	s_nop 1
	global_atomic_add v1, v1, v5, s[6:7] sc0
	s_waitcnt vmcnt(0) lgkmcnt(0)
	v_readfirstlane_b32 s12, v1
	v_readfirstlane_b32 s9, v2
	v_readfirstlane_b32 s10, v3
	s_add_u32 s12, s12, 1
	s_mul_i32 s9, s9, s98
	s_mul_i32 s10, s10, s98
	v_mov_b32_e32 v1, 0x3400
	s_cmp_eq_u32 s12, s9
	s_cbranch_scc0 .Lfs3_spin
	buffer_wbl2 sc1
	s_waitcnt vmcnt(0)
	global_atomic_add v1, v5, s[6:7]

.LBB0_1199:
	s_or_b64 exec, exec, s[0:1]
	s_waitcnt lgkmcnt(0)
	s_barrier
	s_barrier
	s_setprio 0
	s_and_saveexec_b64 s[0:1], s[38:39]
	s_cbranch_execz .LBB0_1201
	s_add_i32 s2, 0, 0x25e20
	v_mov_b32_e32 v1, 0
	s_waitcnt vmcnt(2)
	v_mov_b32_e32 v2, s2
	ds_write_b32 v2, v1

.LBB0_1221:
	s_cmp_gt_i32 s83, 8
	s_cselect_b64 s[0:1], -1, 0
	s_and_b64 s[4:5], s[4:5], s[0:1]
	s_andn2_b64 vcc, exec, s[4:5]
	s_mov_b64 s[60:61], s[38:39]
	s_cbranch_vccnz .LBB0_1275
	s_waitcnt vmcnt(0)
	s_waitcnt vmcnt(0) lgkmcnt(0)
	s_barrier
	s_setprio 0
	s_and_saveexec_b64 s[4:5], s[38:39]
	s_cbranch_execz .LBB0_1274
	s_add_u32 s98, s98, 1
	v_mov_b32_e32 v1, 0x25f20
	ds_read_b64 v[2:3], v1
	v_readlane_b32 s6, v238, 18
	v_readlane_b32 s7, v238, 19
	s_lshl_b32 s2, s87, 8
	s_addk_i32 s2, 0x1400
	v_mov_b32_e32 v1, s2
	v_mov_b32_e32 v5, 1
	s_nop 1
	global_atomic_add v1, v1, v5, s[6:7] sc0
	s_waitcnt vmcnt(0) lgkmcnt(0)
	v_readfirstlane_b32 s12, v1
	v_readfirstlane_b32 s9, v2
	v_readfirstlane_b32 s10, v3
	s_add_u32 s12, s12, 1
	s_mul_i32 s9, s9, s98
	s_mul_i32 s10, s10, s98
	v_mov_b32_e32 v1, 0x3400
	s_cmp_eq_u32 s12, s9
	s_cbranch_scc0 .Lfs4_spin
	buffer_wbl2 sc1
	s_waitcnt vmcnt(0)
	global_atomic_add v1, v5, s[6:7]

.LBB0_1279:
	s_cmp_gt_i32 s83, 9
	s_cselect_b64 s[0:1], -1, 0
	s_and_b64 s[4:5], s[6:7], s[0:1]
	s_andn2_b64 vcc, exec, s[4:5]
	s_cbranch_vccnz .LBB0_1333
	s_waitcnt vmcnt(0)
	s_waitcnt vmcnt(0) lgkmcnt(0)
	s_barrier
	s_setprio 0
	s_and_saveexec_b64 s[4:5], s[38:39]
	s_cbranch_execz .LBB0_1332
	s_add_u32 s98, s98, 1
	v_mov_b32_e32 v1, 0x25f20
	ds_read_b64 v[2:3], v1
	v_readlane_b32 s6, v238, 18
	v_readlane_b32 s7, v238, 19
	s_lshl_b32 s2, s87, 8
	s_addk_i32 s2, 0x1400
	v_mov_b32_e32 v1, s2
	v_mov_b32_e32 v5, 1
	s_nop 1
	global_atomic_add v1, v1, v5, s[6:7] sc0
	s_waitcnt vmcnt(0) lgkmcnt(0)
	v_readfirstlane_b32 s12, v1
	v_readfirstlane_b32 s9, v2
	v_readfirstlane_b32 s10, v3
	s_add_u32 s12, s12, 1
	s_mul_i32 s9, s9, s98
	s_mul_i32 s10, s10, s98
	v_mov_b32_e32 v1, 0x3400
	s_cmp_eq_u32 s12, s9
	s_cbranch_scc0 .Lfs5_spin
	buffer_wbl2 sc1
	s_waitcnt vmcnt(0)
	global_atomic_add v1, v5, s[6:7]

.LBB0_1339:
	s_ashr_i32 s0, s6, 3
	s_add_u32 s33, s80, 0x17b00000
	s_addc_u32 s34, s81, 0
	s_add_u32 s35, s80, 0x2000000
	s_waitcnt vmcnt(0)
	v_lshrrev_b32_e32 v4, 1, v0
	v_lshrrev_b32_e32 v6, 5, v0
	s_addc_u32 s36, s81, 0
	v_lshlrev_b32_e32 v1, 4, v0
	v_and_b32_e32 v2, 32, v0
	v_and_b32_e32 v4, 24, v4
	v_and_b32_e32 v6, 4, v6
	v_bfe_u32 v7, v0, 2, 2
	s_add_i32 s0, s5, s0
	v_bfe_u32 v14, v0, 2, 4
	v_bitop3_b32 v3, v1, v2, 48 bitop3:0x6c
	v_and_b32_e32 v5, 64, v0
	v_or3_b32 v6, v6, v7, v4
	v_lshrrev_b32_e32 v7, 3, v0
	v_or_b32_e32 v15, 0x2000, v1
	s_ashr_i32 s5, s0, 31
	v_or_b32_e32 v2, v3, v5
	v_and_or_b32 v8, v7, 48, v14
	v_and_or_b32 v7, v7, 32, v6
	v_lshrrev_b32_e32 v1, 7, v15
	s_movk_i32 s6, 0x70
	s_lshr_b32 s5, s5, 27
	v_lshl_or_b32 v160, v7, 11, v2
	v_and_or_b32 v7, v1, s6, v14
	s_movk_i32 s6, 0x60
	s_add_i32 s5, s0, s5
	v_and_or_b32 v1, v1, s6, v6
	s_ashr_i32 s6, s5, 5
	s_andn2_b32 s5, s5, 31
	s_sub_i32 s5, s0, s5
	s_bfe_i32 s0, s5, 0x80000
	s_bfe_u32 s0, s0, 0x3000c
	s_add_i32 s7, s5, s0
	s_bfe_i32 s0, s7, 0x80000
	s_and_b32 s7, s7, 0xf8
	s_sub_i32 s5, s5, s7
	s_lshl_b32 s6, s6, 3
	s_sext_i32_i16 s0, s0
	s_sext_i32_i8 s5, s5
	s_lshr_b32 s1, s4, 8
	s_lshr_b32 s0, s0, 3
	s_add_i32 s24, s6, s5
	s_lshr_b32 s10, s4, 6
	s_ashr_i32 s25, s24, 31
	s_bfe_i64 s[8:9], s[0:1], 0x100000
	s_lshl_b32 s37, s10, 10
	s_lshl_b64 s[6:7], s[24:25], 19
	s_lshl_b64 s[8:9], s[8:9], 19
	s_add_u32 s26, s35, s8
	s_addc_u32 s27, s36, s9
	s_add_i32 s38, s37, 0
	s_add_i32 m0, s38, 0x10000
	v_lshl_or_b32 v164, v1, 11, v2
	global_load_lds_dwordx4 v160, s[26:27]
	s_add_i32 m0, s38, 0x12000
	s_add_u32 s8, s26, 0x40000
	global_load_lds_dwordx4 v164, s[26:27]
	s_addc_u32 s9, s27, 0
	s_add_i32 m0, s38, 0x14000
	v_lshl_or_b32 v158, v8, 11, v2
	global_load_lds_dwordx4 v160, s[8:9]
	s_add_i32 m0, s38, 0x16000
	s_add_u32 s22, s33, s6
	s_addc_u32 s23, s34, s7
	s_add_i32 s39, s38, 0x2000
	global_load_lds_dwordx4 v164, s[8:9]
	s_mov_b32 m0, s38
	s_add_u32 s6, s22, 0x40000
	v_lshl_or_b32 v162, v7, 11, v2
	global_load_lds_dwordx4 v158, s[22:23]
	s_mov_b32 m0, s39
	s_addc_u32 s7, s23, 0
	s_add_i32 s40, s38, 0x4000
	global_load_lds_dwordx4 v162, s[22:23]
	s_mov_b32 m0, s40
	s_add_i32 s41, s38, 0x6000
	global_load_lds_dwordx4 v158, s[6:7]
	s_mov_b32 m0, s41
	v_mov_b32_e32 v2, 0
	global_load_lds_dwordx4 v162, s[6:7]
	v_mov_b32_e32 v161, v2
	v_mov_b32_e32 v165, v2
	v_mov_b32_e32 v159, v2
	v_mov_b32_e32 v163, v2
	s_cmp_eq_u32 s1, 1
	s_mov_b32 s5, 0
	v_lshl_add_u64 v[12:13], s[26:27], 0, v[160:161]
	v_lshl_add_u64 v[10:11], s[26:27], 0, v[164:165]
	v_lshl_add_u64 v[6:7], s[22:23], 0, v[158:159]
	s_cselect_b64 s[6:7], -1, 0
	s_cmp_lg_u32 s1, 1
	v_lshl_add_u64 v[8:9], s[22:23], 0, v[162:163]
	s_cbranch_scc1 .LBB0_1341
	s_setprio 1
	s_barrier

.LBB0_1351:
	s_add_u32 s28, s22, s26
	s_addc_u32 s29, s23, s27
	s_add_u32 s28, s28, 0x100
	s_addc_u32 s29, s29, 0
	s_add_u32 s55, s25, s26
	s_addc_u32 s56, s53, s27
	s_add_i32 s57, 0, 0x10000
	v_add_u32_e32 v3, s57, v186
	ds_read_b128 v[134:137], v3
	ds_read_b128 v[138:141], v3 offset:1024
	ds_read_b128 v[142:145], v3 offset:2048
	ds_read_b128 v[146:149], v3 offset:3072
	v_add_u32_e32 v3, s49, v186
	ds_read_b128 v[150:153], v3
	ds_read_b128 v[154:157], v3 offset:1024
	ds_read_b128 v[190:193], v3 offset:2048
	ds_read_b128 v[194:197], v3 offset:3072
	s_cmpk_eq_i32 s26, 0x700
	s_cselect_b32 s31, s17, s29
	s_cselect_b32 s30, s51, s28
	s_cselect_b32 s29, s15, s56
	s_cselect_b32 s28, s52, s55
	v_lshl_add_u64 v[4:5], v[182:183], 0, s[26:27]
	s_add_i32 m0, s38, 0xc000
	ds_read_b128 v[198:201], v188
	ds_read_b128 v[202:205], v188 offset:1024
	ds_read_b128 v[206:209], v188 offset:2048
	ds_read_b128 v[210:213], v188 offset:3072
	ds_read_b128 v[214:217], v188 offset:4096
	ds_read_b128 v[218:221], v188 offset:5120
	ds_read_b128 v[222:225], v188 offset:6144
	ds_read_b128 v[226:229], v188 offset:7168
	global_load_lds_dwordx4 v[4:5], off
	v_lshl_add_u64 v[4:5], v[184:185], 0, s[26:27]
	s_add_i32 m0, s38, 0xe000
	s_nop 0
	global_load_lds_dwordx4 v[4:5], off
	s_waitcnt vmcnt(8)
	s_waitcnt lgkmcnt(0)
	s_barrier
	s_waitcnt lgkmcnt(0)
	v_mfma_f32_16x16x32_bf16 v[130:133], v[134:137], v[198:201], v[130:133]
	v_mfma_f32_16x16x32_bf16 v[126:129], v[142:145], v[198:201], v[126:129]
	v_mfma_f32_16x16x32_bf16 v[114:117], v[134:137], v[206:209], v[114:117]
	v_mfma_f32_16x16x32_bf16 v[110:113], v[142:145], v[206:209], v[110:113]
	v_mfma_f32_16x16x32_bf16 v[98:101], v[134:137], v[214:217], v[98:101]
	v_mfma_f32_16x16x32_bf16 v[94:97], v[142:145], v[214:217], v[94:97]
	v_mfma_f32_16x16x32_bf16 v[82:85], v[134:137], v[222:225], v[82:85]
	v_mfma_f32_16x16x32_bf16 v[78:81], v[142:145], v[222:225], v[78:81]
	v_mfma_f32_16x16x32_bf16 v[130:133], v[138:141], v[202:205], v[130:133]
	v_mfma_f32_16x16x32_bf16 v[126:129], v[146:149], v[202:205], v[126:129]
	v_mfma_f32_16x16x32_bf16 v[114:117], v[138:141], v[210:213], v[114:117]
	v_mfma_f32_16x16x32_bf16 v[110:113], v[146:149], v[210:213], v[110:113]
	v_mfma_f32_16x16x32_bf16 v[98:101], v[138:141], v[218:221], v[98:101]
	v_mfma_f32_16x16x32_bf16 v[94:97], v[146:149], v[218:221], v[94:97]
	v_mfma_f32_16x16x32_bf16 v[82:85], v[138:141], v[226:229], v[82:85]
	v_mfma_f32_16x16x32_bf16 v[78:81], v[146:149], v[226:229], v[78:81]
	v_mfma_f32_16x16x32_bf16 v[122:125], v[150:153], v[198:201], v[122:125]
	v_mfma_f32_16x16x32_bf16 v[118:121], v[190:193], v[198:201], v[118:121]
	v_mfma_f32_16x16x32_bf16 v[106:109], v[150:153], v[206:209], v[106:109]
	v_mfma_f32_16x16x32_bf16 v[102:105], v[190:193], v[206:209], v[102:105]
	v_mfma_f32_16x16x32_bf16 v[90:93], v[150:153], v[214:217], v[90:93]
	v_mfma_f32_16x16x32_bf16 v[86:89], v[190:193], v[214:217], v[86:89]
	v_mfma_f32_16x16x32_bf16 v[74:77], v[150:153], v[222:225], v[74:77]
	v_mfma_f32_16x16x32_bf16 v[70:73], v[190:193], v[222:225], v[70:73]
	v_mfma_f32_16x16x32_bf16 v[122:125], v[154:157], v[202:205], v[122:125]
	v_mfma_f32_16x16x32_bf16 v[118:121], v[194:197], v[202:205], v[118:121]
	v_mfma_f32_16x16x32_bf16 v[106:109], v[154:157], v[210:213], v[106:109]
	v_mfma_f32_16x16x32_bf16 v[102:105], v[194:197], v[210:213], v[102:105]
	v_mfma_f32_16x16x32_bf16 v[90:93], v[154:157], v[218:221], v[90:93]
	v_mfma_f32_16x16x32_bf16 v[86:89], v[194:197], v[218:221], v[86:89]
	v_mfma_f32_16x16x32_bf16 v[74:77], v[154:157], v[226:229], v[74:77]
	v_mfma_f32_16x16x32_bf16 v[70:73], v[194:197], v[226:229], v[70:73]
	s_barrier
	s_add_i32 s55, s57, s37
	v_lshl_add_u64 v[230:231], s[28:29], 0, v[160:161]
	s_mov_b32 m0, s55
	ds_read_b128 v[198:201], v188 offset:16384
	ds_read_b128 v[202:205], v188 offset:17408
	ds_read_b128 v[206:209], v188 offset:18432
	ds_read_b128 v[210:213], v188 offset:19456
	ds_read_b128 v[214:217], v188 offset:20480
	ds_read_b128 v[218:221], v188 offset:21504
	ds_read_b128 v[222:225], v188 offset:22528
	ds_read_b128 v[226:229], v188 offset:23552
	global_load_lds_dwordx4 v[230:231], off
	s_add_i32 m0, s55, 0x2000
	s_add_u32 s56, s28, 0x40000
	v_lshl_add_u64 v[232:233], s[28:29], 0, v[164:165]
	s_addc_u32 s57, s29, 0
	s_add_i32 s55, s49, s37
	global_load_lds_dwordx4 v[232:233], off
	v_lshl_add_u64 v[4:5], s[56:57], 0, v[160:161]
	s_mov_b32 m0, s55
	v_lshl_add_u64 v[234:235], s[30:31], 0, v[158:159]
	global_load_lds_dwordx4 v[4:5], off
	v_lshl_add_u64 v[4:5], s[56:57], 0, v[164:165]
	s_add_i32 m0, s55, 0x2000
	v_lshl_add_u64 v[236:237], s[30:31], 0, v[162:163]
	global_load_lds_dwordx4 v[4:5], off
	s_mov_b32 m0, s38
	s_nop 0
	global_load_lds_dwordx4 v[234:235], off
	s_mov_b32 m0, s39
	s_nop 0
	global_load_lds_dwordx4 v[236:237], off
	s_waitcnt vmcnt(8)
	s_waitcnt lgkmcnt(0)
	s_barrier
	s_waitcnt lgkmcnt(0)
	v_mfma_f32_16x16x32_bf16 v[66:69], v[134:137], v[198:201], v[66:69]
	v_mfma_f32_16x16x32_bf16 v[62:65], v[142:145], v[198:201], v[62:65]
	v_mfma_f32_16x16x32_bf16 v[50:53], v[134:137], v[206:209], v[50:53]
	v_mfma_f32_16x16x32_bf16 v[46:49], v[142:145], v[206:209], v[46:49]
	v_mfma_f32_16x16x32_bf16 v[34:37], v[134:137], v[214:217], v[34:37]
	v_mfma_f32_16x16x32_bf16 v[30:33], v[142:145], v[214:217], v[30:33]
	v_mfma_f32_16x16x32_bf16 v[18:21], v[134:137], v[222:225], v[18:21]
	v_mfma_f32_16x16x32_bf16 v[14:17], v[142:145], v[222:225], v[14:17]
	v_mfma_f32_16x16x32_bf16 v[66:69], v[138:141], v[202:205], v[66:69]
	v_mfma_f32_16x16x32_bf16 v[62:65], v[146:149], v[202:205], v[62:65]
	v_mfma_f32_16x16x32_bf16 v[50:53], v[138:141], v[210:213], v[50:53]
	v_mfma_f32_16x16x32_bf16 v[46:49], v[146:149], v[210:213], v[46:49]
	v_mfma_f32_16x16x32_bf16 v[34:37], v[138:141], v[218:221], v[34:37]
	v_mfma_f32_16x16x32_bf16 v[30:33], v[146:149], v[218:221], v[30:33]
	v_mfma_f32_16x16x32_bf16 v[18:21], v[138:141], v[226:229], v[18:21]
	v_mfma_f32_16x16x32_bf16 v[14:17], v[146:149], v[226:229], v[14:17]
	v_mfma_f32_16x16x32_bf16 v[58:61], v[150:153], v[198:201], v[58:61]
	v_mfma_f32_16x16x32_bf16 v[54:57], v[190:193], v[198:201], v[54:57]
	v_mfma_f32_16x16x32_bf16 v[42:45], v[150:153], v[206:209], v[42:45]
	v_mfma_f32_16x16x32_bf16 v[38:41], v[190:193], v[206:209], v[38:41]
	v_mfma_f32_16x16x32_bf16 v[26:29], v[150:153], v[214:217], v[26:29]
	v_mfma_f32_16x16x32_bf16 v[22:25], v[190:193], v[214:217], v[22:25]
	v_mfma_f32_16x16x32_bf16 v[10:13], v[150:153], v[222:225], v[10:13]
	v_mfma_f32_16x16x32_bf16 v[4:7], v[190:193], v[222:225], v[6:9]
	v_mfma_f32_16x16x32_bf16 v[58:61], v[154:157], v[202:205], v[58:61]
	v_mfma_f32_16x16x32_bf16 v[54:57], v[194:197], v[202:205], v[54:57]
	v_mfma_f32_16x16x32_bf16 v[42:45], v[154:157], v[210:213], v[42:45]
	v_mfma_f32_16x16x32_bf16 v[38:41], v[194:197], v[210:213], v[38:41]
	v_mfma_f32_16x16x32_bf16 v[26:29], v[154:157], v[218:221], v[26:29]
	v_mfma_f32_16x16x32_bf16 v[22:25], v[194:197], v[218:221], v[22:25]
	v_mfma_f32_16x16x32_bf16 v[10:13], v[154:157], v[226:229], v[10:13]
	v_mfma_f32_16x16x32_bf16 v[4:7], v[194:197], v[226:229], v[4:7]
	s_barrier
	s_add_i32 s55, 0, 0x18000
	v_add_u32_e32 v3, s55, v186
	s_add_i32 s56, 0, 0x1c000
	ds_read_b128 v[134:137], v3
	ds_read_b128 v[138:141], v3 offset:1024
	ds_read_b128 v[142:145], v3 offset:2048
	ds_read_b128 v[146:149], v3 offset:3072
	v_add_u32_e32 v3, s56, v186
	ds_read_b128 v[150:153], v3
	ds_read_b128 v[154:157], v3 offset:1024
	ds_read_b128 v[190:193], v3 offset:2048
	ds_read_b128 v[194:197], v3 offset:3072
	s_add_u32 s30, s30, 0x40000
	s_addc_u32 s31, s31, 0
	s_mov_b32 m0, s40
	v_lshl_add_u64 v[8:9], s[30:31], 0, v[158:159]
	ds_read_b128 v[198:201], v188 offset:32768
	ds_read_b128 v[202:205], v188 offset:33792
	ds_read_b128 v[206:209], v188 offset:34816
	ds_read_b128 v[210:213], v188 offset:35840
	ds_read_b128 v[214:217], v188 offset:36864
	ds_read_b128 v[218:221], v188 offset:37888
	ds_read_b128 v[222:225], v188 offset:38912
	ds_read_b128 v[226:229], v188 offset:39936
	global_load_lds_dwordx4 v[8:9], off
	v_lshl_add_u64 v[8:9], s[30:31], 0, v[162:163]
	s_mov_b32 m0, s41
	s_nop 0
	global_load_lds_dwordx4 v[8:9], off
	s_waitcnt vmcnt(8)
	s_waitcnt lgkmcnt(0)
	s_barrier
	s_waitcnt lgkmcnt(0)
	v_mfma_f32_16x16x32_bf16 v[130:133], v[134:137], v[198:201], v[130:133]
	v_mfma_f32_16x16x32_bf16 v[126:129], v[142:145], v[198:201], v[126:129]
	v_mfma_f32_16x16x32_bf16 v[114:117], v[134:137], v[206:209], v[114:117]
	v_mfma_f32_16x16x32_bf16 v[110:113], v[142:145], v[206:209], v[110:113]
	v_mfma_f32_16x16x32_bf16 v[98:101], v[134:137], v[214:217], v[98:101]
	v_mfma_f32_16x16x32_bf16 v[94:97], v[142:145], v[214:217], v[94:97]
	v_mfma_f32_16x16x32_bf16 v[82:85], v[134:137], v[222:225], v[82:85]
	v_mfma_f32_16x16x32_bf16 v[78:81], v[142:145], v[222:225], v[78:81]
	v_mfma_f32_16x16x32_bf16 v[130:133], v[138:141], v[202:205], v[130:133]
	v_mfma_f32_16x16x32_bf16 v[126:129], v[146:149], v[202:205], v[126:129]
	v_mfma_f32_16x16x32_bf16 v[114:117], v[138:141], v[210:213], v[114:117]
	v_mfma_f32_16x16x32_bf16 v[110:113], v[146:149], v[210:213], v[110:113]
	v_mfma_f32_16x16x32_bf16 v[98:101], v[138:141], v[218:221], v[98:101]
	v_mfma_f32_16x16x32_bf16 v[94:97], v[146:149], v[218:221], v[94:97]
	v_mfma_f32_16x16x32_bf16 v[82:85], v[138:141], v[226:229], v[82:85]
	v_mfma_f32_16x16x32_bf16 v[78:81], v[146:149], v[226:229], v[78:81]
	v_mfma_f32_16x16x32_bf16 v[122:125], v[150:153], v[198:201], v[122:125]
	v_mfma_f32_16x16x32_bf16 v[118:121], v[190:193], v[198:201], v[118:121]
	v_mfma_f32_16x16x32_bf16 v[106:109], v[150:153], v[206:209], v[106:109]
	v_mfma_f32_16x16x32_bf16 v[102:105], v[190:193], v[206:209], v[102:105]
	v_mfma_f32_16x16x32_bf16 v[90:93], v[150:153], v[214:217], v[90:93]
	v_mfma_f32_16x16x32_bf16 v[86:89], v[190:193], v[214:217], v[86:89]
	v_mfma_f32_16x16x32_bf16 v[74:77], v[150:153], v[222:225], v[74:77]
	v_mfma_f32_16x16x32_bf16 v[70:73], v[190:193], v[222:225], v[70:73]
	v_mfma_f32_16x16x32_bf16 v[122:125], v[154:157], v[202:205], v[122:125]
	v_mfma_f32_16x16x32_bf16 v[118:121], v[194:197], v[202:205], v[118:121]
	v_mfma_f32_16x16x32_bf16 v[106:109], v[154:157], v[210:213], v[106:109]
	v_mfma_f32_16x16x32_bf16 v[102:105], v[194:197], v[210:213], v[102:105]
	v_mfma_f32_16x16x32_bf16 v[90:93], v[154:157], v[218:221], v[90:93]
	v_mfma_f32_16x16x32_bf16 v[86:89], v[194:197], v[218:221], v[86:89]
	v_mfma_f32_16x16x32_bf16 v[74:77], v[154:157], v[226:229], v[74:77]
	v_mfma_f32_16x16x32_bf16 v[70:73], v[194:197], v[226:229], v[70:73]
	s_barrier
	s_add_i32 s30, s55, s37
	v_lshl_add_u64 v[8:9], v[230:231], 0, s[10:11]
	s_mov_b32 m0, s30
	ds_read_b128 v[198:201], v188 offset:49152
	ds_read_b128 v[202:205], v188 offset:50176
	ds_read_b128 v[206:209], v188 offset:51200
	ds_read_b128 v[210:213], v188 offset:52224
	ds_read_b128 v[214:217], v188 offset:53248
	ds_read_b128 v[218:221], v188 offset:54272
	ds_read_b128 v[222:225], v188 offset:55296
	ds_read_b128 v[226:229], v188 offset:56320
	global_load_lds_dwordx4 v[8:9], off
	s_add_i32 m0, s30, 0x2000
	s_add_u32 s28, s28, 0x40080
	v_lshl_add_u64 v[8:9], v[232:233], 0, s[10:11]
	s_addc_u32 s29, s29, 0
	s_add_i32 s30, s56, s37
	global_load_lds_dwordx4 v[8:9], off
	v_lshl_add_u64 v[8:9], s[28:29], 0, v[160:161]
	s_mov_b32 m0, s30
	s_nop 0
	global_load_lds_dwordx4 v[8:9], off
	v_lshl_add_u64 v[8:9], s[28:29], 0, v[164:165]
	s_add_i32 m0, s30, 0x2000
	s_nop 0
	global_load_lds_dwordx4 v[8:9], off
	v_lshl_add_u64 v[8:9], v[234:235], 0, s[10:11]
	s_mov_b32 m0, s42
	s_nop 0
	global_load_lds_dwordx4 v[8:9], off
	v_lshl_add_u64 v[8:9], v[236:237], 0, s[10:11]
	s_mov_b32 m0, s43
	s_nop 0
	global_load_lds_dwordx4 v[8:9], off
	s_waitcnt vmcnt(8)
	s_waitcnt lgkmcnt(0)
	s_barrier
	s_waitcnt lgkmcnt(0)
	v_mfma_f32_16x16x32_bf16 v[66:69], v[134:137], v[198:201], v[66:69]
	v_mfma_f32_16x16x32_bf16 v[62:65], v[142:145], v[198:201], v[62:65]
	v_mfma_f32_16x16x32_bf16 v[50:53], v[134:137], v[206:209], v[50:53]
	v_mfma_f32_16x16x32_bf16 v[46:49], v[142:145], v[206:209], v[46:49]
	v_mfma_f32_16x16x32_bf16 v[34:37], v[134:137], v[214:217], v[34:37]
	v_mfma_f32_16x16x32_bf16 v[30:33], v[142:145], v[214:217], v[30:33]
	v_mfma_f32_16x16x32_bf16 v[18:21], v[134:137], v[222:225], v[18:21]
	v_mfma_f32_16x16x32_bf16 v[14:17], v[142:145], v[222:225], v[14:17]
	v_mfma_f32_16x16x32_bf16 v[66:69], v[138:141], v[202:205], v[66:69]
	v_mfma_f32_16x16x32_bf16 v[62:65], v[146:149], v[202:205], v[62:65]
	v_mfma_f32_16x16x32_bf16 v[50:53], v[138:141], v[210:213], v[50:53]
	v_mfma_f32_16x16x32_bf16 v[46:49], v[146:149], v[210:213], v[46:49]
	v_mfma_f32_16x16x32_bf16 v[34:37], v[138:141], v[218:221], v[34:37]
	v_mfma_f32_16x16x32_bf16 v[30:33], v[146:149], v[218:221], v[30:33]
	v_mfma_f32_16x16x32_bf16 v[18:21], v[138:141], v[226:229], v[18:21]
	v_mfma_f32_16x16x32_bf16 v[14:17], v[146:149], v[226:229], v[14:17]
	v_mfma_f32_16x16x32_bf16 v[58:61], v[150:153], v[198:201], v[58:61]
	v_mfma_f32_16x16x32_bf16 v[54:57], v[190:193], v[198:201], v[54:57]
	v_mfma_f32_16x16x32_bf16 v[42:45], v[150:153], v[206:209], v[42:45]
	v_mfma_f32_16x16x32_bf16 v[38:41], v[190:193], v[206:209], v[38:41]
	v_mfma_f32_16x16x32_bf16 v[26:29], v[150:153], v[214:217], v[26:29]
	v_mfma_f32_16x16x32_bf16 v[22:25], v[190:193], v[214:217], v[22:25]
	v_mfma_f32_16x16x32_bf16 v[8:11], v[150:153], v[222:225], v[10:13]
	v_mfma_f32_16x16x32_bf16 v[4:7], v[190:193], v[222:225], v[4:7]
	v_mfma_f32_16x16x32_bf16 v[58:61], v[154:157], v[202:205], v[58:61]
	v_mfma_f32_16x16x32_bf16 v[54:57], v[194:197], v[202:205], v[54:57]
	v_mfma_f32_16x16x32_bf16 v[42:45], v[154:157], v[210:213], v[42:45]
	v_mfma_f32_16x16x32_bf16 v[38:41], v[194:197], v[210:213], v[38:41]
	v_mfma_f32_16x16x32_bf16 v[26:29], v[154:157], v[218:221], v[26:29]
	v_mfma_f32_16x16x32_bf16 v[22:25], v[194:197], v[218:221], v[22:25]
	v_mfma_f32_16x16x32_bf16 v[10:13], v[154:157], v[226:229], v[8:11]
	v_mfma_f32_16x16x32_bf16 v[6:9], v[194:197], v[226:229], v[4:7]
	s_barrier
	s_add_i32 s54, s54, 2
	s_add_u32 s26, s26, 0x100
	s_addc_u32 s27, s27, 0
	s_cmp_gt_u32 s54, 13
	s_cbranch_scc1 .LBB0_1354

.LBB0_1360:
	s_cmp_lt_i32 s82, 11
	s_cselect_b64 s[4:5], -1, 0
	s_cmp_gt_i32 s83, 11
	s_cselect_b64 s[0:1], -1, 0
	s_and_b64 s[4:5], s[4:5], s[0:1]
	s_andn2_b64 vcc, exec, s[4:5]
	s_cbranch_vccnz .LBB0_1414
	s_waitcnt vmcnt(0)
	s_waitcnt vmcnt(0) lgkmcnt(0)
	s_barrier
	s_setprio 0
	s_and_saveexec_b64 s[4:5], s[38:39]
	s_cbranch_execz .LBB0_1413
	s_add_u32 s98, s98, 1
	v_mov_b32_e32 v1, 0x25f20
	ds_read_b64 v[2:3], v1
	v_readlane_b32 s6, v238, 18
	v_readlane_b32 s7, v238, 19
	s_lshl_b32 s2, s87, 8
	s_addk_i32 s2, 0x1400
	v_mov_b32_e32 v1, s2
	v_mov_b32_e32 v5, 1
	s_nop 1
	global_atomic_add v1, v1, v5, s[6:7] sc0
	s_waitcnt vmcnt(0) lgkmcnt(0)
	v_readfirstlane_b32 s12, v1
	v_readfirstlane_b32 s9, v2
	v_readfirstlane_b32 s10, v3
	s_add_u32 s12, s12, 1
	s_mul_i32 s9, s9, s98
	s_mul_i32 s10, s10, s98
	v_mov_b32_e32 v1, 0x3400
	s_cmp_eq_u32 s12, s9
	s_cbranch_scc0 .Lfs6_spin
	buffer_wbl2 sc1
	s_waitcnt vmcnt(0)
	global_atomic_add v1, v5, s[6:7]

.LBB0_1421:
	s_andn2_b64 vcc, exec, s[0:1]
	s_cbranch_vccnz .LBB0_1457
	s_waitcnt vmcnt(0)
	v_lshrrev_b32_e32 v3, 1, v0
	v_lshrrev_b32_e32 v4, 5, v0
	s_add_u32 s2, s80, 0x2400000
	v_lshlrev_b32_e32 v1, 4, v0
	v_and_b32_e32 v2, 32, v0
	v_and_b32_e32 v3, 24, v3
	v_and_b32_e32 v4, 4, v4
	v_bfe_u32 v5, v0, 2, 2
	s_addc_u32 s33, s81, 0
	v_bfe_u32 v12, v0, 2, 4
	v_bitop3_b32 v10, v1, v2, 48 bitop3:0x6c
	v_and_b32_e32 v11, 64, v0
	v_or3_b32 v3, v4, v5, v3
	v_lshrrev_b32_e32 v4, 3, v0
	v_or_b32_e32 v13, 0x2000, v1
	s_add_u32 s38, s80, 0x1e00000
	v_or_b32_e32 v2, v10, v11
	v_and_or_b32 v5, v4, 48, v12
	v_and_or_b32 v4, v4, 32, v3
	v_lshrrev_b32_e32 v1, 7, v13
	s_movk_i32 s0, 0x70
	s_addc_u32 s39, s81, 0
	s_lshr_b32 s1, s18, 6
	v_lshl_or_b32 v148, v4, 11, v2
	v_and_or_b32 v4, v1, s0, v12
	s_movk_i32 s0, 0x60
	s_ashr_i32 s29, s28, 31
	s_ashr_i32 s9, s8, 31
	v_and_or_b32 v1, v1, s0, v3
	s_lshr_b32 s0, s18, 8
	s_lshl_b32 s40, s1, 10
	s_lshl_b64 s[4:5], s[28:29], 19
	s_lshl_b64 s[10:11], s[8:9], 19
	s_add_u32 s34, s38, s10
	s_addc_u32 s35, s39, s11
	s_add_i32 s41, s40, 0
	s_add_i32 m0, s41, 0x10000
	v_lshl_or_b32 v152, v1, 11, v2
	global_load_lds_dwordx4 v148, s[34:35]
	s_add_i32 m0, s41, 0x12000
	s_add_u32 s10, s34, 0x40000
	global_load_lds_dwordx4 v152, s[34:35]
	s_addc_u32 s11, s35, 0
	s_add_i32 m0, s41, 0x14000
	v_lshl_or_b32 v146, v5, 11, v2
	global_load_lds_dwordx4 v148, s[10:11]
	s_add_i32 m0, s41, 0x16000
	s_add_u32 s30, s2, s4
	s_addc_u32 s31, s33, s5
	s_add_i32 s42, s41, 0x2000
	global_load_lds_dwordx4 v152, s[10:11]
	s_mov_b32 m0, s41
	s_add_u32 s4, s30, 0x40000
	v_lshl_or_b32 v150, v4, 11, v2
	global_load_lds_dwordx4 v146, s[30:31]
	s_mov_b32 m0, s42
	s_addc_u32 s5, s31, 0
	s_add_i32 s43, s41, 0x4000
	global_load_lds_dwordx4 v150, s[30:31]
	s_mov_b32 m0, s43
	s_add_i32 s44, s41, 0x6000
	global_load_lds_dwordx4 v146, s[4:5]
	s_mov_b32 m0, s44
	v_mov_b32_e32 v149, 0
	global_load_lds_dwordx4 v150, s[4:5]
	v_mov_b32_e32 v153, v149
	v_mov_b32_e32 v147, v149
	v_mov_b32_e32 v151, v149
	s_cmp_eq_u32 s0, 1
	s_mov_b32 s9, 0
	v_lshl_add_u64 v[8:9], s[34:35], 0, v[148:149]
	v_lshl_add_u64 v[6:7], s[34:35], 0, v[152:153]
	v_lshl_add_u64 v[2:3], s[30:31], 0, v[146:147]
	s_cselect_b64 s[10:11], -1, 0
	s_cmp_lg_u32 s0, 1
	v_lshl_add_u64 v[4:5], s[30:31], 0, v[150:151]
	s_cbranch_scc1 .LBB0_1424
	s_setprio 1
	s_barrier

.LBB0_1434:
	ds_read_b128 v[130:133], v172
	ds_read_b128 v[134:137], v172 offset:1024
	ds_read_b128 v[138:141], v172 offset:2048
	ds_read_b128 v[142:145], v172 offset:3072
	ds_read_b128 v[162:165], v173
	ds_read_b128 v[166:169], v173 offset:1024
	ds_read_b128 v[176:179], v173 offset:2048
	ds_read_b128 v[180:183], v173 offset:3072
	s_add_u32 s34, s30, 0xfffc0080
	s_addc_u32 s35, s31, -1
	s_cmp_eq_u32 s56, 12
	s_cselect_b32 s37, s23, s35
	s_cselect_b32 s36, s29, s34
	s_cselect_b32 s35, s21, s55
	s_cselect_b32 s34, s53, s54
	v_lshl_add_u64 v[216:217], s[30:31], 0, v[154:155]
	s_add_i32 m0, s41, 0xc000
	ds_read_b128 v[184:187], v174
	ds_read_b128 v[188:191], v174 offset:1024
	ds_read_b128 v[192:195], v174 offset:2048
	ds_read_b128 v[196:199], v174 offset:3072
	ds_read_b128 v[200:203], v174 offset:4096
	ds_read_b128 v[204:207], v174 offset:5120
	ds_read_b128 v[208:211], v174 offset:6144
	ds_read_b128 v[212:215], v174 offset:7168
	global_load_lds_dwordx4 v[216:217], off
	v_lshl_add_u64 v[216:217], s[30:31], 0, v[156:157]
	s_add_i32 m0, s41, 0xe000
	s_nop 0
	global_load_lds_dwordx4 v[216:217], off
	s_waitcnt vmcnt(8)
	s_waitcnt lgkmcnt(0)
	s_barrier
	s_waitcnt lgkmcnt(0)
	v_mfma_f32_16x16x32_bf16 v[126:129], v[130:133], v[184:187], v[126:129]
	v_mfma_f32_16x16x32_bf16 v[122:125], v[138:141], v[184:187], v[122:125]
	v_mfma_f32_16x16x32_bf16 v[110:113], v[130:133], v[192:195], v[110:113]
	v_mfma_f32_16x16x32_bf16 v[106:109], v[138:141], v[192:195], v[106:109]
	v_mfma_f32_16x16x32_bf16 v[94:97], v[130:133], v[200:203], v[94:97]
	v_mfma_f32_16x16x32_bf16 v[90:93], v[138:141], v[200:203], v[90:93]
	v_mfma_f32_16x16x32_bf16 v[78:81], v[130:133], v[208:211], v[78:81]
	v_mfma_f32_16x16x32_bf16 v[74:77], v[138:141], v[208:211], v[74:77]
	v_mfma_f32_16x16x32_bf16 v[126:129], v[134:137], v[188:191], v[126:129]
	v_mfma_f32_16x16x32_bf16 v[122:125], v[142:145], v[188:191], v[122:125]
	v_mfma_f32_16x16x32_bf16 v[110:113], v[134:137], v[196:199], v[110:113]
	v_mfma_f32_16x16x32_bf16 v[106:109], v[142:145], v[196:199], v[106:109]
	v_mfma_f32_16x16x32_bf16 v[94:97], v[134:137], v[204:207], v[94:97]
	v_mfma_f32_16x16x32_bf16 v[90:93], v[142:145], v[204:207], v[90:93]
	v_mfma_f32_16x16x32_bf16 v[78:81], v[134:137], v[212:215], v[78:81]
	v_mfma_f32_16x16x32_bf16 v[74:77], v[142:145], v[212:215], v[74:77]
	v_mfma_f32_16x16x32_bf16 v[118:121], v[162:165], v[184:187], v[118:121]
	v_mfma_f32_16x16x32_bf16 v[114:117], v[176:179], v[184:187], v[114:117]
	v_mfma_f32_16x16x32_bf16 v[102:105], v[162:165], v[192:195], v[102:105]
	v_mfma_f32_16x16x32_bf16 v[98:101], v[176:179], v[192:195], v[98:101]
	v_mfma_f32_16x16x32_bf16 v[86:89], v[162:165], v[200:203], v[86:89]
	v_mfma_f32_16x16x32_bf16 v[82:85], v[176:179], v[200:203], v[82:85]
	v_mfma_f32_16x16x32_bf16 v[70:73], v[162:165], v[208:211], v[70:73]
	v_mfma_f32_16x16x32_bf16 v[66:69], v[176:179], v[208:211], v[66:69]
	v_mfma_f32_16x16x32_bf16 v[118:121], v[166:169], v[188:191], v[118:121]
	v_mfma_f32_16x16x32_bf16 v[114:117], v[180:183], v[188:191], v[114:117]
	v_mfma_f32_16x16x32_bf16 v[102:105], v[166:169], v[196:199], v[102:105]
	v_mfma_f32_16x16x32_bf16 v[98:101], v[180:183], v[196:199], v[98:101]
	v_mfma_f32_16x16x32_bf16 v[86:89], v[166:169], v[204:207], v[86:89]
	v_mfma_f32_16x16x32_bf16 v[82:85], v[180:183], v[204:207], v[82:85]
	v_mfma_f32_16x16x32_bf16 v[70:73], v[166:169], v[212:215], v[70:73]
	v_mfma_f32_16x16x32_bf16 v[66:69], v[180:183], v[212:215], v[66:69]
	s_barrier
	s_add_i32 s57, s50, s40
	v_lshl_add_u64 v[216:217], s[34:35], 0, v[148:149]
	s_mov_b32 m0, s57
	ds_read_b128 v[184:187], v174 offset:16384
	ds_read_b128 v[188:191], v174 offset:17408
	ds_read_b128 v[192:195], v174 offset:18432
	ds_read_b128 v[196:199], v174 offset:19456
	ds_read_b128 v[200:203], v174 offset:20480
	ds_read_b128 v[204:207], v174 offset:21504
	ds_read_b128 v[208:211], v174 offset:22528
	ds_read_b128 v[212:215], v174 offset:23552
	global_load_lds_dwordx4 v[216:217], off
	s_add_i32 m0, s57, 0x2000
	s_add_u32 s58, s34, 0x40000
	v_lshl_add_u64 v[218:219], s[34:35], 0, v[152:153]
	s_addc_u32 s59, s35, 0
	s_add_i32 s57, s51, s40
	global_load_lds_dwordx4 v[218:219], off
	v_lshl_add_u64 v[220:221], s[58:59], 0, v[148:149]
	s_mov_b32 m0, s57
	v_lshl_add_u64 v[222:223], s[36:37], 0, v[150:151]
	global_load_lds_dwordx4 v[220:221], off
	v_lshl_add_u64 v[220:221], s[58:59], 0, v[152:153]
	s_add_i32 m0, s57, 0x2000
	s_nop 0
	global_load_lds_dwordx4 v[220:221], off
	v_lshl_add_u64 v[220:221], s[36:37], 0, v[146:147]
	s_mov_b32 m0, s41
	s_nop 0
	global_load_lds_dwordx4 v[220:221], off
	s_mov_b32 m0, s42
	s_nop 0
	global_load_lds_dwordx4 v[222:223], off
	s_waitcnt vmcnt(8)
	s_waitcnt lgkmcnt(0)
	s_barrier
	s_waitcnt lgkmcnt(0)
	v_mfma_f32_16x16x32_bf16 v[62:65], v[130:133], v[184:187], v[62:65]
	v_mfma_f32_16x16x32_bf16 v[58:61], v[138:141], v[184:187], v[58:61]
	v_mfma_f32_16x16x32_bf16 v[46:49], v[130:133], v[192:195], v[46:49]
	v_mfma_f32_16x16x32_bf16 v[42:45], v[138:141], v[192:195], v[42:45]
	v_mfma_f32_16x16x32_bf16 v[30:33], v[130:133], v[200:203], v[30:33]
	v_mfma_f32_16x16x32_bf16 v[26:29], v[138:141], v[200:203], v[26:29]
	v_mfma_f32_16x16x32_bf16 v[14:17], v[130:133], v[208:211], v[14:17]
	v_mfma_f32_16x16x32_bf16 v[10:13], v[138:141], v[208:211], v[10:13]
	v_mfma_f32_16x16x32_bf16 v[62:65], v[134:137], v[188:191], v[62:65]
	v_mfma_f32_16x16x32_bf16 v[58:61], v[142:145], v[188:191], v[58:61]
	v_mfma_f32_16x16x32_bf16 v[46:49], v[134:137], v[196:199], v[46:49]
	v_mfma_f32_16x16x32_bf16 v[42:45], v[142:145], v[196:199], v[42:45]
	v_mfma_f32_16x16x32_bf16 v[30:33], v[134:137], v[204:207], v[30:33]
	v_mfma_f32_16x16x32_bf16 v[26:29], v[142:145], v[204:207], v[26:29]
	v_mfma_f32_16x16x32_bf16 v[14:17], v[134:137], v[212:215], v[14:17]
	v_mfma_f32_16x16x32_bf16 v[10:13], v[142:145], v[212:215], v[10:13]
	v_mfma_f32_16x16x32_bf16 v[54:57], v[162:165], v[184:187], v[54:57]
	v_mfma_f32_16x16x32_bf16 v[50:53], v[176:179], v[184:187], v[50:53]
	v_mfma_f32_16x16x32_bf16 v[38:41], v[162:165], v[192:195], v[38:41]
	v_mfma_f32_16x16x32_bf16 v[34:37], v[176:179], v[192:195], v[34:37]
	v_mfma_f32_16x16x32_bf16 v[22:25], v[162:165], v[200:203], v[22:25]
	v_mfma_f32_16x16x32_bf16 v[18:21], v[176:179], v[200:203], v[18:21]
	v_mfma_f32_16x16x32_bf16 v[6:9], v[162:165], v[208:211], v[6:9]
	v_mfma_f32_16x16x32_bf16 v[2:5], v[176:179], v[208:211], v[2:5]
	v_mfma_f32_16x16x32_bf16 v[54:57], v[166:169], v[188:191], v[54:57]
	v_mfma_f32_16x16x32_bf16 v[50:53], v[180:183], v[188:191], v[50:53]
	v_mfma_f32_16x16x32_bf16 v[38:41], v[166:169], v[196:199], v[38:41]
	v_mfma_f32_16x16x32_bf16 v[34:37], v[180:183], v[196:199], v[34:37]
	v_mfma_f32_16x16x32_bf16 v[22:25], v[166:169], v[204:207], v[22:25]
	v_mfma_f32_16x16x32_bf16 v[18:21], v[180:183], v[204:207], v[18:21]
	v_mfma_f32_16x16x32_bf16 v[6:9], v[166:169], v[212:215], v[6:9]
	v_mfma_f32_16x16x32_bf16 v[2:5], v[180:183], v[212:215], v[2:5]
	s_barrier
	s_add_i32 s57, 0, 0x18000
	s_add_i32 s58, 0, 0x1c000
	v_add_u32_e32 v142, s57, v170
	v_add_u32_e32 v175, s58, v170
	ds_read_b128 v[130:133], v142
	ds_read_b128 v[134:137], v142 offset:1024
	ds_read_b128 v[138:141], v142 offset:2048
	ds_read_b128 v[142:145], v142 offset:3072
	ds_read_b128 v[162:165], v175
	ds_read_b128 v[166:169], v175 offset:1024
	ds_read_b128 v[176:179], v175 offset:2048
	ds_read_b128 v[180:183], v175 offset:3072
	s_add_u32 s36, s36, 0x40000
	s_addc_u32 s37, s37, 0
	s_mov_b32 m0, s43
	v_lshl_add_u64 v[224:225], s[36:37], 0, v[146:147]
	ds_read_b128 v[184:187], v174 offset:32768
	ds_read_b128 v[188:191], v174 offset:33792
	ds_read_b128 v[192:195], v174 offset:34816
	ds_read_b128 v[196:199], v174 offset:35840
	ds_read_b128 v[200:203], v174 offset:36864
	ds_read_b128 v[204:207], v174 offset:37888
	ds_read_b128 v[208:211], v174 offset:38912
	ds_read_b128 v[212:215], v174 offset:39936
	global_load_lds_dwordx4 v[224:225], off
	v_lshl_add_u64 v[224:225], s[36:37], 0, v[150:151]
	s_mov_b32 m0, s44
	s_nop 0
	global_load_lds_dwordx4 v[224:225], off
	s_waitcnt vmcnt(8)
	s_waitcnt lgkmcnt(0)
	s_barrier
	s_waitcnt lgkmcnt(0)
	v_mfma_f32_16x16x32_bf16 v[126:129], v[130:133], v[184:187], v[126:129]
	v_mfma_f32_16x16x32_bf16 v[122:125], v[138:141], v[184:187], v[122:125]
	v_mfma_f32_16x16x32_bf16 v[110:113], v[130:133], v[192:195], v[110:113]
	v_mfma_f32_16x16x32_bf16 v[106:109], v[138:141], v[192:195], v[106:109]
	v_mfma_f32_16x16x32_bf16 v[94:97], v[130:133], v[200:203], v[94:97]
	v_mfma_f32_16x16x32_bf16 v[90:93], v[138:141], v[200:203], v[90:93]
	v_mfma_f32_16x16x32_bf16 v[78:81], v[130:133], v[208:211], v[78:81]
	v_mfma_f32_16x16x32_bf16 v[74:77], v[138:141], v[208:211], v[74:77]
	v_mfma_f32_16x16x32_bf16 v[126:129], v[134:137], v[188:191], v[126:129]
	v_mfma_f32_16x16x32_bf16 v[122:125], v[142:145], v[188:191], v[122:125]
	v_mfma_f32_16x16x32_bf16 v[110:113], v[134:137], v[196:199], v[110:113]
	v_mfma_f32_16x16x32_bf16 v[106:109], v[142:145], v[196:199], v[106:109]
	v_mfma_f32_16x16x32_bf16 v[94:97], v[134:137], v[204:207], v[94:97]
	v_mfma_f32_16x16x32_bf16 v[90:93], v[142:145], v[204:207], v[90:93]
	v_mfma_f32_16x16x32_bf16 v[78:81], v[134:137], v[212:215], v[78:81]
	v_mfma_f32_16x16x32_bf16 v[74:77], v[142:145], v[212:215], v[74:77]
	v_mfma_f32_16x16x32_bf16 v[118:121], v[162:165], v[184:187], v[118:121]
	v_mfma_f32_16x16x32_bf16 v[114:117], v[176:179], v[184:187], v[114:117]
	v_mfma_f32_16x16x32_bf16 v[102:105], v[162:165], v[192:195], v[102:105]
	v_mfma_f32_16x16x32_bf16 v[98:101], v[176:179], v[192:195], v[98:101]
	v_mfma_f32_16x16x32_bf16 v[86:89], v[162:165], v[200:203], v[86:89]
	v_mfma_f32_16x16x32_bf16 v[82:85], v[176:179], v[200:203], v[82:85]
	v_mfma_f32_16x16x32_bf16 v[70:73], v[162:165], v[208:211], v[70:73]
	v_mfma_f32_16x16x32_bf16 v[66:69], v[176:179], v[208:211], v[66:69]
	v_mfma_f32_16x16x32_bf16 v[118:121], v[166:169], v[188:191], v[118:121]
	v_mfma_f32_16x16x32_bf16 v[114:117], v[180:183], v[188:191], v[114:117]
	v_mfma_f32_16x16x32_bf16 v[102:105], v[166:169], v[196:199], v[102:105]
	v_mfma_f32_16x16x32_bf16 v[98:101], v[180:183], v[196:199], v[98:101]
	v_mfma_f32_16x16x32_bf16 v[86:89], v[166:169], v[204:207], v[86:89]
	v_mfma_f32_16x16x32_bf16 v[82:85], v[180:183], v[204:207], v[82:85]
	v_mfma_f32_16x16x32_bf16 v[70:73], v[166:169], v[212:215], v[70:73]
	v_mfma_f32_16x16x32_bf16 v[66:69], v[180:183], v[212:215], v[66:69]
	s_barrier
	s_add_i32 s36, s57, s40
	v_lshl_add_u64 v[216:217], v[216:217], 0, s[16:17]
	s_mov_b32 m0, s36
	ds_read_b128 v[184:187], v174 offset:49152
	ds_read_b128 v[188:191], v174 offset:50176
	ds_read_b128 v[192:195], v174 offset:51200
	ds_read_b128 v[196:199], v174 offset:52224
	ds_read_b128 v[200:203], v174 offset:53248
	ds_read_b128 v[204:207], v174 offset:54272
	ds_read_b128 v[208:211], v174 offset:55296
	ds_read_b128 v[212:215], v174 offset:56320
	global_load_lds_dwordx4 v[216:217], off
	s_add_i32 m0, s36, 0x2000
	s_add_u32 s34, s34, 0x40080
	v_lshl_add_u64 v[216:217], v[218:219], 0, s[16:17]
	s_addc_u32 s35, s35, 0
	s_add_i32 s36, s58, s40
	global_load_lds_dwordx4 v[216:217], off
	v_lshl_add_u64 v[216:217], s[34:35], 0, v[148:149]
	s_mov_b32 m0, s36
	s_nop 0
	global_load_lds_dwordx4 v[216:217], off
	v_lshl_add_u64 v[216:217], s[34:35], 0, v[152:153]
	s_add_i32 m0, s36, 0x2000
	s_nop 0
	global_load_lds_dwordx4 v[216:217], off
	v_lshl_add_u64 v[216:217], v[220:221], 0, s[16:17]
	s_mov_b32 m0, s46
	s_nop 0
	global_load_lds_dwordx4 v[216:217], off
	v_lshl_add_u64 v[216:217], v[222:223], 0, s[16:17]
	s_mov_b32 m0, s47
	s_nop 0
	global_load_lds_dwordx4 v[216:217], off
	s_waitcnt vmcnt(8)
	s_waitcnt lgkmcnt(0)
	s_barrier
	s_waitcnt lgkmcnt(0)
	v_mfma_f32_16x16x32_bf16 v[62:65], v[130:133], v[184:187], v[62:65]
	v_mfma_f32_16x16x32_bf16 v[58:61], v[138:141], v[184:187], v[58:61]
	v_mfma_f32_16x16x32_bf16 v[46:49], v[130:133], v[192:195], v[46:49]
	v_mfma_f32_16x16x32_bf16 v[42:45], v[138:141], v[192:195], v[42:45]
	v_mfma_f32_16x16x32_bf16 v[30:33], v[130:133], v[200:203], v[30:33]
	v_mfma_f32_16x16x32_bf16 v[26:29], v[138:141], v[200:203], v[26:29]
	v_mfma_f32_16x16x32_bf16 v[14:17], v[130:133], v[208:211], v[14:17]
	v_mfma_f32_16x16x32_bf16 v[10:13], v[138:141], v[208:211], v[10:13]
	v_mfma_f32_16x16x32_bf16 v[62:65], v[134:137], v[188:191], v[62:65]
	v_mfma_f32_16x16x32_bf16 v[58:61], v[142:145], v[188:191], v[58:61]
	v_mfma_f32_16x16x32_bf16 v[46:49], v[134:137], v[196:199], v[46:49]
	v_mfma_f32_16x16x32_bf16 v[42:45], v[142:145], v[196:199], v[42:45]
	v_mfma_f32_16x16x32_bf16 v[30:33], v[134:137], v[204:207], v[30:33]
	v_mfma_f32_16x16x32_bf16 v[26:29], v[142:145], v[204:207], v[26:29]
	v_mfma_f32_16x16x32_bf16 v[14:17], v[134:137], v[212:215], v[14:17]
	v_mfma_f32_16x16x32_bf16 v[10:13], v[142:145], v[212:215], v[10:13]
	v_mfma_f32_16x16x32_bf16 v[54:57], v[162:165], v[184:187], v[54:57]
	v_mfma_f32_16x16x32_bf16 v[50:53], v[176:179], v[184:187], v[50:53]
	v_mfma_f32_16x16x32_bf16 v[38:41], v[162:165], v[192:195], v[38:41]
	v_mfma_f32_16x16x32_bf16 v[34:37], v[176:179], v[192:195], v[34:37]
	v_mfma_f32_16x16x32_bf16 v[22:25], v[162:165], v[200:203], v[22:25]
	v_mfma_f32_16x16x32_bf16 v[18:21], v[176:179], v[200:203], v[18:21]
	v_mfma_f32_16x16x32_bf16 v[6:9], v[162:165], v[208:211], v[6:9]
	v_mfma_f32_16x16x32_bf16 v[2:5], v[176:179], v[208:211], v[2:5]
	v_mfma_f32_16x16x32_bf16 v[54:57], v[166:169], v[188:191], v[54:57]
	v_mfma_f32_16x16x32_bf16 v[50:53], v[180:183], v[188:191], v[50:53]
	v_mfma_f32_16x16x32_bf16 v[38:41], v[166:169], v[196:199], v[38:41]
	v_mfma_f32_16x16x32_bf16 v[34:37], v[180:183], v[196:199], v[34:37]
	v_mfma_f32_16x16x32_bf16 v[22:25], v[166:169], v[204:207], v[22:25]
	v_mfma_f32_16x16x32_bf16 v[18:21], v[180:183], v[204:207], v[18:21]
	v_mfma_f32_16x16x32_bf16 v[6:9], v[166:169], v[212:215], v[6:9]
	v_mfma_f32_16x16x32_bf16 v[2:5], v[180:183], v[212:215], v[2:5]
	s_barrier
	s_add_i32 s56, s56, 2
	s_add_u32 s30, s30, 0x100
	s_addc_u32 s31, s31, 0
	s_add_u32 s54, s54, 0x100
	s_addc_u32 s55, s55, 0
	s_cmp_gt_u32 s56, 13
	s_cbranch_scc0 .LBB0_1434
	s_and_b64 vcc, exec, s[18:19]
	s_cbranch_vccz .LBB0_1437
	s_barrier

.LBB0_1457:
	s_cmp_gt_i32 s83, 12
	s_cselect_b64 s[0:1], -1, 0
	s_and_b64 s[4:5], s[6:7], s[0:1]
	s_andn2_b64 vcc, exec, s[4:5]
	s_cbranch_vccnz .LBB0_1511
	s_waitcnt vmcnt(0)
	s_waitcnt vmcnt(0) lgkmcnt(0)
	s_barrier
	s_setprio 0
	s_and_saveexec_b64 s[4:5], s[38:39]
	s_cbranch_execz .LBB0_1510
	s_add_u32 s98, s98, 1
	v_mov_b32_e32 v1, 0x25f20
	ds_read_b64 v[2:3], v1
	v_readlane_b32 s6, v238, 18
	v_readlane_b32 s7, v238, 19
	s_lshl_b32 s2, s87, 8
	s_addk_i32 s2, 0x1400
	v_mov_b32_e32 v1, s2
	v_mov_b32_e32 v5, 1
	s_nop 1
	global_atomic_add v1, v1, v5, s[6:7] sc0
	s_waitcnt vmcnt(0) lgkmcnt(0)
	v_readfirstlane_b32 s12, v1
	v_readfirstlane_b32 s9, v2
	v_readfirstlane_b32 s10, v3
	s_add_u32 s12, s12, 1
	s_mul_i32 s9, s9, s98
	s_mul_i32 s10, s10, s98
	v_mov_b32_e32 v1, 0x3400
	s_cmp_eq_u32 s12, s9
	s_cbranch_scc0 .Lfs7_spin
	buffer_wbl2 sc1
	s_waitcnt vmcnt(0)
	global_atomic_add v1, v5, s[6:7]

.LBB0_1511:
	s_mov_b32 s99, -1
	s_cmp_lt_i32 s82, 13
	s_cselect_b64 s[4:5], -1, 0
	s_and_b64 s[4:5], s[4:5], s[0:1]
	s_andn2_b64 vcc, exec, s[4:5]
	s_cbranch_vccnz .LBB0_1528
	s_cmpk_gt_i32 s86, 0xaff
	v_readfirstlane_b32 s1, v0
	s_cbranch_scc1 .LBB0_1528
	s_waitcnt vmcnt(0)
	v_lshrrev_b32_e32 v1, 5, v0
	v_lshrrev_b32_e32 v3, 1, v0
	v_and_b32_e32 v1, 4, v1
	v_bfe_u32 v2, v0, 2, 2
	v_and_b32_e32 v3, 24, v3
	s_add_u32 s2, s80, 0xa900000
	v_or3_b32 v1, v1, v2, v3
	v_lshlrev_b32_e32 v2, 4, v0
	s_addc_u32 s30, s81, 0
	v_or_b32_e32 v10, 0x2000, v2
	s_add_u32 s31, s80, 0xd00000
	v_lshrrev_b32_e32 v3, 7, v10
	s_movk_i32 s0, 0x60
	s_addc_u32 s33, s81, 0
	v_and_or_b32 v4, v3, s0, v1
	v_bfe_u32 v13, v0, 2, 4
	s_movk_i32 s0, 0x70
	s_ashr_i32 s35, s86, 31
	v_and_or_b32 v3, v3, s0, v13
	s_lshr_b32 s0, s35, 29
	s_add_i32 s0, s86, s0
	s_lshr_b32 s10, s1, 6
	s_ashr_i32 s6, s0, 3
	s_and_b32 s0, s0, -8
	s_lshr_b32 s12, s1, 8
	s_lshl_b32 s34, s10, 10
	s_sub_i32 s0, s86, s0
	s_cmp_lt_i32 s0, 0
	s_movk_i32 s36, 0x161
	s_cselect_b32 s7, s36, 0x160
	s_mul_i32 s0, s7, s0
	s_add_i32 s0, s0, s6
	s_mul_hi_i32 s6, s0, 0x2e8ba2e9
	s_lshr_b32 s7, s6, 31
	s_ashr_i32 s6, s6, 5
	s_add_i32 s6, s6, s7
	s_lshl_b32 s7, s6, 3
	s_mulk_i32 s6, 0xb0
	s_sub_i32 s6, s0, s6
	s_sext_i32_i16 s0, s6
	s_bfe_u32 s0, s0, 0x3001c
	s_add_i32 s8, s6, s0
	s_sext_i32_i16 s0, s8
	s_and_b32 s8, s8, 0xfff8
	s_sub_i32 s6, s6, s8
	s_sext_i32_i16 s6, s6
	v_and_b32_e32 v5, 32, v0
	s_lshr_b32 s0, s0, 3
	s_add_i32 s22, s7, s6
	v_bitop3_b32 v11, v2, v5, 48 bitop3:0x6c
	v_and_b32_e32 v12, 64, v0
	s_ashr_i32 s23, s22, 31
	s_bfe_i64 s[8:9], s[0:1], 0x100000
	v_or_b32_e32 v2, v11, v12
	s_lshl_b64 s[6:7], s[22:23], 19
	s_lshl_b64 s[8:9], s[8:9], 19
	v_lshl_or_b32 v156, v3, 11, v2
	v_lshrrev_b32_e32 v3, 3, v0
	s_add_u32 s26, s31, s8
	v_and_or_b32 v1, v3, 32, v1
	s_addc_u32 s27, s33, s9
	s_add_i32 s23, s34, 0
	v_lshl_or_b32 v158, v1, 11, v2
	s_add_i32 m0, s23, 0x10000
	v_lshl_or_b32 v154, v4, 11, v2
	global_load_lds_dwordx4 v158, s[26:27]
	s_add_i32 m0, s23, 0x12000
	s_add_u32 s8, s26, 0x40000
	global_load_lds_dwordx4 v154, s[26:27]
	s_addc_u32 s9, s27, 0
	s_add_i32 m0, s23, 0x14000
	v_and_or_b32 v1, v3, 48, v13
	global_load_lds_dwordx4 v158, s[8:9]
	s_add_i32 m0, s23, 0x16000
	s_add_u32 s24, s2, s6
	s_addc_u32 s25, s30, s7
	s_add_i32 s37, s23, 0x2000
	v_lshl_or_b32 v160, v1, 11, v2
	global_load_lds_dwordx4 v154, s[8:9]
	s_mov_b32 m0, s23
	s_add_u32 s6, s24, 0x40000
	global_load_lds_dwordx4 v160, s[24:25]
	s_mov_b32 m0, s37
	s_addc_u32 s7, s25, 0
	s_add_i32 s38, s23, 0x4000
	global_load_lds_dwordx4 v156, s[24:25]
	s_mov_b32 m0, s38
	s_add_i32 s39, s23, 0x6000
	global_load_lds_dwordx4 v160, s[6:7]
	s_mov_b32 m0, s39
	v_mov_b32_e32 v159, 0
	global_load_lds_dwordx4 v156, s[6:7]
	v_mov_b32_e32 v155, v159
	v_mov_b32_e32 v161, v159
	v_mov_b32_e32 v157, v159
	s_cmp_eq_u32 s12, 1
	s_mov_b32 s40, 0
	v_lshl_add_u64 v[8:9], s[26:27], 0, v[158:159]
	v_lshl_add_u64 v[6:7], s[26:27], 0, v[154:155]
	v_lshl_add_u64 v[2:3], s[24:25], 0, v[160:161]
	s_cselect_b64 s[6:7], -1, 0
	s_cmp_lg_u32 s12, 1
	v_lshl_add_u64 v[4:5], s[24:25], 0, v[156:157]
	s_cbranch_scc1 .LBB0_1515
	s_setprio 1
	s_barrier

.LBB0_1521:
	ds_read_b128 v[130:133], v190
	ds_read_b128 v[134:137], v190 offset:1024
	ds_read_b128 v[138:141], v190 offset:2048
	ds_read_b128 v[142:145], v190 offset:3072
	ds_read_b128 v[146:149], v191
	ds_read_b128 v[150:153], v191 offset:1024
	ds_read_b128 v[172:175], v191 offset:2048
	ds_read_b128 v[176:179], v191 offset:3072
	s_add_u32 s26, s24, 0xfffc0080
	s_addc_u32 s27, s25, -1
	s_cmp_eq_u32 s53, 12
	s_cselect_b32 s29, s17, s27
	s_cselect_b32 s28, s49, s26
	s_cselect_b32 s27, s15, s52
	s_cselect_b32 s26, s50, s51
	v_lshl_add_u64 v[218:219], s[24:25], 0, v[164:165]
	s_add_i32 m0, s23, 0xc000
	ds_read_b128 v[180:183], v192
	ds_read_b128 v[184:187], v192 offset:1024
	ds_read_b128 v[194:197], v192 offset:2048
	ds_read_b128 v[198:201], v192 offset:3072
	ds_read_b128 v[202:205], v192 offset:4096
	ds_read_b128 v[206:209], v192 offset:5120
	ds_read_b128 v[210:213], v192 offset:6144
	ds_read_b128 v[214:217], v192 offset:7168
	global_load_lds_dwordx4 v[218:219], off
	v_lshl_add_u64 v[218:219], s[24:25], 0, v[166:167]
	s_add_i32 m0, s23, 0xe000
	s_nop 0
	global_load_lds_dwordx4 v[218:219], off
	s_waitcnt vmcnt(8)
	s_waitcnt lgkmcnt(0)
	s_barrier
	s_waitcnt lgkmcnt(0)
	v_mfma_f32_16x16x32_bf16 v[126:129], v[130:133], v[180:183], v[126:129]
	v_mfma_f32_16x16x32_bf16 v[122:125], v[138:141], v[180:183], v[122:125]
	v_mfma_f32_16x16x32_bf16 v[110:113], v[130:133], v[194:197], v[110:113]
	v_mfma_f32_16x16x32_bf16 v[106:109], v[138:141], v[194:197], v[106:109]
	v_mfma_f32_16x16x32_bf16 v[94:97], v[130:133], v[202:205], v[94:97]
	v_mfma_f32_16x16x32_bf16 v[90:93], v[138:141], v[202:205], v[90:93]
	v_mfma_f32_16x16x32_bf16 v[78:81], v[130:133], v[210:213], v[78:81]
	v_mfma_f32_16x16x32_bf16 v[74:77], v[138:141], v[210:213], v[74:77]
	v_mfma_f32_16x16x32_bf16 v[126:129], v[134:137], v[184:187], v[126:129]
	v_mfma_f32_16x16x32_bf16 v[122:125], v[142:145], v[184:187], v[122:125]
	v_mfma_f32_16x16x32_bf16 v[110:113], v[134:137], v[198:201], v[110:113]
	v_mfma_f32_16x16x32_bf16 v[106:109], v[142:145], v[198:201], v[106:109]
	v_mfma_f32_16x16x32_bf16 v[94:97], v[134:137], v[206:209], v[94:97]
	v_mfma_f32_16x16x32_bf16 v[90:93], v[142:145], v[206:209], v[90:93]
	v_mfma_f32_16x16x32_bf16 v[78:81], v[134:137], v[214:217], v[78:81]
	v_mfma_f32_16x16x32_bf16 v[74:77], v[142:145], v[214:217], v[74:77]
	v_mfma_f32_16x16x32_bf16 v[118:121], v[146:149], v[180:183], v[118:121]
	v_mfma_f32_16x16x32_bf16 v[114:117], v[172:175], v[180:183], v[114:117]
	v_mfma_f32_16x16x32_bf16 v[102:105], v[146:149], v[194:197], v[102:105]
	v_mfma_f32_16x16x32_bf16 v[98:101], v[172:175], v[194:197], v[98:101]
	v_mfma_f32_16x16x32_bf16 v[86:89], v[146:149], v[202:205], v[86:89]
	v_mfma_f32_16x16x32_bf16 v[82:85], v[172:175], v[202:205], v[82:85]
	v_mfma_f32_16x16x32_bf16 v[70:73], v[146:149], v[210:213], v[70:73]
	v_mfma_f32_16x16x32_bf16 v[66:69], v[172:175], v[210:213], v[66:69]
	v_mfma_f32_16x16x32_bf16 v[118:121], v[150:153], v[184:187], v[118:121]
	v_mfma_f32_16x16x32_bf16 v[114:117], v[176:179], v[184:187], v[114:117]
	v_mfma_f32_16x16x32_bf16 v[102:105], v[150:153], v[198:201], v[102:105]
	v_mfma_f32_16x16x32_bf16 v[98:101], v[176:179], v[198:201], v[98:101]
	v_mfma_f32_16x16x32_bf16 v[86:89], v[150:153], v[206:209], v[86:89]
	v_mfma_f32_16x16x32_bf16 v[82:85], v[176:179], v[206:209], v[82:85]
	v_mfma_f32_16x16x32_bf16 v[70:73], v[150:153], v[214:217], v[70:73]
	v_mfma_f32_16x16x32_bf16 v[66:69], v[176:179], v[214:217], v[66:69]
	s_barrier
	s_add_i32 s54, s44, s34
	v_lshl_add_u64 v[218:219], s[26:27], 0, v[158:159]
	s_mov_b32 m0, s54
	ds_read_b128 v[180:183], v192 offset:16384
	ds_read_b128 v[184:187], v192 offset:17408
	ds_read_b128 v[194:197], v192 offset:18432
	ds_read_b128 v[198:201], v192 offset:19456
	ds_read_b128 v[202:205], v192 offset:20480
	ds_read_b128 v[206:209], v192 offset:21504
	ds_read_b128 v[210:213], v192 offset:22528
	ds_read_b128 v[214:217], v192 offset:23552
	global_load_lds_dwordx4 v[218:219], off
	s_add_i32 m0, s54, 0x2000
	s_add_u32 s54, s26, 0x40000
	v_lshl_add_u64 v[220:221], s[26:27], 0, v[154:155]
	s_addc_u32 s55, s27, 0
	s_add_i32 s56, s45, s34
	global_load_lds_dwordx4 v[220:221], off
	v_lshl_add_u64 v[222:223], s[54:55], 0, v[158:159]
	s_mov_b32 m0, s56
	v_lshl_add_u64 v[224:225], s[28:29], 0, v[156:157]
	global_load_lds_dwordx4 v[222:223], off
	v_lshl_add_u64 v[222:223], s[54:55], 0, v[154:155]
	s_add_i32 m0, s56, 0x2000
	s_nop 0
	global_load_lds_dwordx4 v[222:223], off
	v_lshl_add_u64 v[222:223], s[28:29], 0, v[160:161]
	s_mov_b32 m0, s23
	s_nop 0
	global_load_lds_dwordx4 v[222:223], off
	s_mov_b32 m0, s37
	s_nop 0
	global_load_lds_dwordx4 v[224:225], off
	s_waitcnt vmcnt(8)
	s_waitcnt lgkmcnt(0)
	s_barrier
	s_waitcnt lgkmcnt(0)
	v_mfma_f32_16x16x32_bf16 v[62:65], v[130:133], v[180:183], v[62:65]
	v_mfma_f32_16x16x32_bf16 v[58:61], v[138:141], v[180:183], v[58:61]
	v_mfma_f32_16x16x32_bf16 v[46:49], v[130:133], v[194:197], v[46:49]
	v_mfma_f32_16x16x32_bf16 v[42:45], v[138:141], v[194:197], v[42:45]
	v_mfma_f32_16x16x32_bf16 v[30:33], v[130:133], v[202:205], v[30:33]
	v_mfma_f32_16x16x32_bf16 v[26:29], v[138:141], v[202:205], v[26:29]
	v_mfma_f32_16x16x32_bf16 v[14:17], v[130:133], v[210:213], v[14:17]
	v_mfma_f32_16x16x32_bf16 v[10:13], v[138:141], v[210:213], v[10:13]
	v_mfma_f32_16x16x32_bf16 v[62:65], v[134:137], v[184:187], v[62:65]
	v_mfma_f32_16x16x32_bf16 v[58:61], v[142:145], v[184:187], v[58:61]
	v_mfma_f32_16x16x32_bf16 v[46:49], v[134:137], v[198:201], v[46:49]
	v_mfma_f32_16x16x32_bf16 v[42:45], v[142:145], v[198:201], v[42:45]
	v_mfma_f32_16x16x32_bf16 v[30:33], v[134:137], v[206:209], v[30:33]
	v_mfma_f32_16x16x32_bf16 v[26:29], v[142:145], v[206:209], v[26:29]
	v_mfma_f32_16x16x32_bf16 v[14:17], v[134:137], v[214:217], v[14:17]
	v_mfma_f32_16x16x32_bf16 v[10:13], v[142:145], v[214:217], v[10:13]
	v_mfma_f32_16x16x32_bf16 v[54:57], v[146:149], v[180:183], v[54:57]
	v_mfma_f32_16x16x32_bf16 v[50:53], v[172:175], v[180:183], v[50:53]
	v_mfma_f32_16x16x32_bf16 v[38:41], v[146:149], v[194:197], v[38:41]
	v_mfma_f32_16x16x32_bf16 v[34:37], v[172:175], v[194:197], v[34:37]
	v_mfma_f32_16x16x32_bf16 v[22:25], v[146:149], v[202:205], v[22:25]
	v_mfma_f32_16x16x32_bf16 v[18:21], v[172:175], v[202:205], v[18:21]
	v_mfma_f32_16x16x32_bf16 v[6:9], v[146:149], v[210:213], v[6:9]
	v_mfma_f32_16x16x32_bf16 v[2:5], v[172:175], v[210:213], v[2:5]
	v_mfma_f32_16x16x32_bf16 v[54:57], v[150:153], v[184:187], v[54:57]
	v_mfma_f32_16x16x32_bf16 v[50:53], v[176:179], v[184:187], v[50:53]
	v_mfma_f32_16x16x32_bf16 v[38:41], v[150:153], v[198:201], v[38:41]
	v_mfma_f32_16x16x32_bf16 v[34:37], v[176:179], v[198:201], v[34:37]
	v_mfma_f32_16x16x32_bf16 v[22:25], v[150:153], v[206:209], v[22:25]
	v_mfma_f32_16x16x32_bf16 v[18:21], v[176:179], v[206:209], v[18:21]
	v_mfma_f32_16x16x32_bf16 v[6:9], v[150:153], v[214:217], v[6:9]
	v_mfma_f32_16x16x32_bf16 v[2:5], v[176:179], v[214:217], v[2:5]
	s_barrier
	s_add_i32 s54, 0, 0x18000
	s_add_i32 s55, 0, 0x1c000
	v_add_u32_e32 v142, s54, v188
	v_add_u32_e32 v176, s55, v188
	ds_read_b128 v[130:133], v142
	ds_read_b128 v[134:137], v142 offset:1024
	ds_read_b128 v[138:141], v142 offset:2048
	ds_read_b128 v[142:145], v142 offset:3072
	ds_read_b128 v[146:149], v176
	ds_read_b128 v[150:153], v176 offset:1024
	ds_read_b128 v[172:175], v176 offset:2048
	ds_read_b128 v[176:179], v176 offset:3072
	s_add_u32 s28, s28, 0x40000
	s_addc_u32 s29, s29, 0
	s_mov_b32 m0, s38
	v_lshl_add_u64 v[226:227], s[28:29], 0, v[160:161]
	ds_read_b128 v[180:183], v192 offset:32768
	ds_read_b128 v[184:187], v192 offset:33792
	ds_read_b128 v[194:197], v192 offset:34816
	ds_read_b128 v[198:201], v192 offset:35840
	ds_read_b128 v[202:205], v192 offset:36864
	ds_read_b128 v[206:209], v192 offset:37888
	ds_read_b128 v[210:213], v192 offset:38912
	ds_read_b128 v[214:217], v192 offset:39936
	global_load_lds_dwordx4 v[226:227], off
	v_lshl_add_u64 v[226:227], s[28:29], 0, v[156:157]
	s_mov_b32 m0, s39
	s_nop 0
	global_load_lds_dwordx4 v[226:227], off
	s_waitcnt vmcnt(8)
	s_waitcnt lgkmcnt(0)
	s_barrier
	s_waitcnt lgkmcnt(0)
	v_mfma_f32_16x16x32_bf16 v[126:129], v[130:133], v[180:183], v[126:129]
	v_mfma_f32_16x16x32_bf16 v[122:125], v[138:141], v[180:183], v[122:125]
	v_mfma_f32_16x16x32_bf16 v[110:113], v[130:133], v[194:197], v[110:113]
	v_mfma_f32_16x16x32_bf16 v[106:109], v[138:141], v[194:197], v[106:109]
	v_mfma_f32_16x16x32_bf16 v[94:97], v[130:133], v[202:205], v[94:97]
	v_mfma_f32_16x16x32_bf16 v[90:93], v[138:141], v[202:205], v[90:93]
	v_mfma_f32_16x16x32_bf16 v[78:81], v[130:133], v[210:213], v[78:81]
	v_mfma_f32_16x16x32_bf16 v[74:77], v[138:141], v[210:213], v[74:77]
	v_mfma_f32_16x16x32_bf16 v[126:129], v[134:137], v[184:187], v[126:129]
	v_mfma_f32_16x16x32_bf16 v[122:125], v[142:145], v[184:187], v[122:125]
	v_mfma_f32_16x16x32_bf16 v[110:113], v[134:137], v[198:201], v[110:113]
	v_mfma_f32_16x16x32_bf16 v[106:109], v[142:145], v[198:201], v[106:109]
	v_mfma_f32_16x16x32_bf16 v[94:97], v[134:137], v[206:209], v[94:97]
	v_mfma_f32_16x16x32_bf16 v[90:93], v[142:145], v[206:209], v[90:93]
	v_mfma_f32_16x16x32_bf16 v[78:81], v[134:137], v[214:217], v[78:81]
	v_mfma_f32_16x16x32_bf16 v[74:77], v[142:145], v[214:217], v[74:77]
	v_mfma_f32_16x16x32_bf16 v[118:121], v[146:149], v[180:183], v[118:121]
	v_mfma_f32_16x16x32_bf16 v[114:117], v[172:175], v[180:183], v[114:117]
	v_mfma_f32_16x16x32_bf16 v[102:105], v[146:149], v[194:197], v[102:105]
	v_mfma_f32_16x16x32_bf16 v[98:101], v[172:175], v[194:197], v[98:101]
	v_mfma_f32_16x16x32_bf16 v[86:89], v[146:149], v[202:205], v[86:89]
	v_mfma_f32_16x16x32_bf16 v[82:85], v[172:175], v[202:205], v[82:85]
	v_mfma_f32_16x16x32_bf16 v[70:73], v[146:149], v[210:213], v[70:73]
	v_mfma_f32_16x16x32_bf16 v[66:69], v[172:175], v[210:213], v[66:69]
	v_mfma_f32_16x16x32_bf16 v[118:121], v[150:153], v[184:187], v[118:121]
	v_mfma_f32_16x16x32_bf16 v[114:117], v[176:179], v[184:187], v[114:117]
	v_mfma_f32_16x16x32_bf16 v[102:105], v[150:153], v[198:201], v[102:105]
	v_mfma_f32_16x16x32_bf16 v[98:101], v[176:179], v[198:201], v[98:101]
	v_mfma_f32_16x16x32_bf16 v[86:89], v[150:153], v[206:209], v[86:89]
	v_mfma_f32_16x16x32_bf16 v[82:85], v[176:179], v[206:209], v[82:85]
	v_mfma_f32_16x16x32_bf16 v[70:73], v[150:153], v[214:217], v[70:73]
	v_mfma_f32_16x16x32_bf16 v[66:69], v[176:179], v[214:217], v[66:69]
	s_barrier
	s_add_i32 s28, s54, s34
	v_lshl_add_u64 v[218:219], v[218:219], 0, s[10:11]
	s_mov_b32 m0, s28
	ds_read_b128 v[180:183], v192 offset:49152
	ds_read_b128 v[184:187], v192 offset:50176
	ds_read_b128 v[194:197], v192 offset:51200
	ds_read_b128 v[198:201], v192 offset:52224
	ds_read_b128 v[202:205], v192 offset:53248
	ds_read_b128 v[206:209], v192 offset:54272
	ds_read_b128 v[210:213], v192 offset:55296
	ds_read_b128 v[214:217], v192 offset:56320
	global_load_lds_dwordx4 v[218:219], off
	s_add_i32 m0, s28, 0x2000
	s_add_u32 s26, s26, 0x40080
	v_lshl_add_u64 v[218:219], v[220:221], 0, s[10:11]
	s_addc_u32 s27, s27, 0
	s_add_i32 s28, s55, s34
	global_load_lds_dwordx4 v[218:219], off
	v_lshl_add_u64 v[218:219], s[26:27], 0, v[158:159]
	s_mov_b32 m0, s28
	s_nop 0
	global_load_lds_dwordx4 v[218:219], off
	v_lshl_add_u64 v[218:219], s[26:27], 0, v[154:155]
	s_add_i32 m0, s28, 0x2000
	s_nop 0
	global_load_lds_dwordx4 v[218:219], off
	v_lshl_add_u64 v[218:219], v[222:223], 0, s[10:11]
	s_mov_b32 m0, s41
	s_nop 0
	global_load_lds_dwordx4 v[218:219], off
	v_lshl_add_u64 v[218:219], v[224:225], 0, s[10:11]
	s_mov_b32 m0, s42
	s_nop 0
	global_load_lds_dwordx4 v[218:219], off
	s_waitcnt vmcnt(8)
	s_waitcnt lgkmcnt(0)
	s_barrier
	s_waitcnt lgkmcnt(0)
	v_mfma_f32_16x16x32_bf16 v[62:65], v[130:133], v[180:183], v[62:65]
	v_mfma_f32_16x16x32_bf16 v[58:61], v[138:141], v[180:183], v[58:61]
	v_mfma_f32_16x16x32_bf16 v[46:49], v[130:133], v[194:197], v[46:49]
	v_mfma_f32_16x16x32_bf16 v[42:45], v[138:141], v[194:197], v[42:45]
	v_mfma_f32_16x16x32_bf16 v[30:33], v[130:133], v[202:205], v[30:33]
	v_mfma_f32_16x16x32_bf16 v[26:29], v[138:141], v[202:205], v[26:29]
	v_mfma_f32_16x16x32_bf16 v[14:17], v[130:133], v[210:213], v[14:17]
	v_mfma_f32_16x16x32_bf16 v[10:13], v[138:141], v[210:213], v[10:13]
	v_mfma_f32_16x16x32_bf16 v[62:65], v[134:137], v[184:187], v[62:65]
	v_mfma_f32_16x16x32_bf16 v[58:61], v[142:145], v[184:187], v[58:61]
	v_mfma_f32_16x16x32_bf16 v[46:49], v[134:137], v[198:201], v[46:49]
	v_mfma_f32_16x16x32_bf16 v[42:45], v[142:145], v[198:201], v[42:45]
	v_mfma_f32_16x16x32_bf16 v[30:33], v[134:137], v[206:209], v[30:33]
	v_mfma_f32_16x16x32_bf16 v[26:29], v[142:145], v[206:209], v[26:29]
	v_mfma_f32_16x16x32_bf16 v[14:17], v[134:137], v[214:217], v[14:17]
	v_mfma_f32_16x16x32_bf16 v[10:13], v[142:145], v[214:217], v[10:13]
	v_mfma_f32_16x16x32_bf16 v[54:57], v[146:149], v[180:183], v[54:57]
	v_mfma_f32_16x16x32_bf16 v[50:53], v[172:175], v[180:183], v[50:53]
	v_mfma_f32_16x16x32_bf16 v[38:41], v[146:149], v[194:197], v[38:41]
	v_mfma_f32_16x16x32_bf16 v[34:37], v[172:175], v[194:197], v[34:37]
	v_mfma_f32_16x16x32_bf16 v[22:25], v[146:149], v[202:205], v[22:25]
	v_mfma_f32_16x16x32_bf16 v[18:21], v[172:175], v[202:205], v[18:21]
	v_mfma_f32_16x16x32_bf16 v[6:9], v[146:149], v[210:213], v[6:9]
	v_mfma_f32_16x16x32_bf16 v[2:5], v[172:175], v[210:213], v[2:5]
	v_mfma_f32_16x16x32_bf16 v[54:57], v[150:153], v[184:187], v[54:57]
	v_mfma_f32_16x16x32_bf16 v[50:53], v[176:179], v[184:187], v[50:53]
	v_mfma_f32_16x16x32_bf16 v[38:41], v[150:153], v[198:201], v[38:41]
	v_mfma_f32_16x16x32_bf16 v[34:37], v[176:179], v[198:201], v[34:37]
	v_mfma_f32_16x16x32_bf16 v[22:25], v[150:153], v[206:209], v[22:25]
	v_mfma_f32_16x16x32_bf16 v[18:21], v[176:179], v[206:209], v[18:21]
	v_mfma_f32_16x16x32_bf16 v[6:9], v[150:153], v[214:217], v[6:9]
	v_mfma_f32_16x16x32_bf16 v[2:5], v[176:179], v[214:217], v[2:5]
	s_barrier
	s_add_i32 s53, s53, 2
	s_add_u32 s24, s24, 0x100
	s_addc_u32 s25, s25, 0
	s_add_u32 s51, s51, 0x100
	s_addc_u32 s52, s52, 0
	s_cmp_gt_u32 s53, 13
	s_cbranch_scc0 .LBB0_1521
	s_and_b64 vcc, exec, s[12:13]
	s_cbranch_vccz .LBB0_1524
	s_barrier

.LBB0_1528:
	s_cmp_gt_i32 s83, 13
	s_cselect_b64 s[0:1], -1, 0
	s_and_b64 s[4:5], s[4:5], s[0:1]
	s_andn2_b64 vcc, exec, s[4:5]
	s_cbranch_vccnz .LBB0_1582
	s_waitcnt vmcnt(0)
	s_waitcnt vmcnt(0) lgkmcnt(0)
	s_barrier
	s_setprio 0
	s_and_saveexec_b64 s[4:5], s[38:39]
	s_cbranch_execz .LBB0_1581
	s_add_u32 s98, s98, 1
	v_mov_b32_e32 v1, 0x25f20
	ds_read_b64 v[2:3], v1
	v_readlane_b32 s6, v238, 18
	v_readlane_b32 s7, v238, 19
	s_lshl_b32 s2, s87, 8
	s_addk_i32 s2, 0x1400
	v_mov_b32_e32 v1, s2
	v_mov_b32_e32 v5, 1
	s_nop 1
	global_atomic_add v1, v1, v5, s[6:7] sc0
	s_waitcnt vmcnt(0) lgkmcnt(0)
	v_readfirstlane_b32 s12, v1
	v_readfirstlane_b32 s9, v2
	v_readfirstlane_b32 s10, v3
	s_add_u32 s12, s12, 1
	s_mul_i32 s9, s9, s98
	s_mul_i32 s10, s10, s98
	v_mov_b32_e32 v1, 0x3400
	s_cmp_eq_u32 s12, s9
	s_cbranch_scc0 .Lfs8_spin
	buffer_wbl2 sc1
	s_waitcnt vmcnt(0)
	global_atomic_add v1, v5, s[6:7]

.LBB0_1588:
	s_add_u32 s22, s80, 0x14b00000
	s_addc_u32 s23, s81, 0
	s_add_u32 s24, s80, 0x1800000
	s_addc_u32 s25, s81, 0
	s_add_i32 s1, s6, s1
	s_ashr_i32 s6, s1, 31
	s_waitcnt vmcnt(0)
	v_lshrrev_b32_e32 v4, 1, v0
	s_lshr_b32 s6, s6, 27
	v_and_b32_e32 v11, 24, v4
	v_lshrrev_b32_e32 v4, 5, v0
	s_add_i32 s6, s1, s6
	v_lshlrev_b32_e32 v1, 4, v0
	v_and_b32_e32 v2, 32, v0
	v_and_b32_e32 v4, 4, v4
	v_bfe_u32 v5, v0, 2, 2
	s_ashr_i32 s7, s6, 5
	s_and_b32 s6, s6, 0xffe0
	v_bfe_u32 v3, v0, 2, 4
	v_bitop3_b32 v1, v1, v2, 48 bitop3:0x6c
	v_and_b32_e32 v10, 64, v0
	v_or3_b32 v4, v4, v5, v11
	v_lshrrev_b32_e32 v5, 3, v0
	s_sub_i32 s6, s1, s6
	v_or_b32_e32 v2, v1, v10
	v_and_or_b32 v6, v5, 48, v3
	v_and_or_b32 v5, v5, 32, v4
	s_bfe_i32 s1, s6, 0x80000
	v_lshrrev_b32_e32 v2, 1, v2
	v_mul_u32_u24_e32 v5, 0xb00, v5
	s_bfe_u32 s1, s1, 0x3000c
	v_or_b32_e32 v5, v5, v2
	s_add_i32 s8, s6, s1
	v_lshlrev_b32_e32 v130, 1, v5
	v_bfe_u32 v5, v0, 3, 25
	s_bfe_i32 s1, s8, 0x80000
	s_and_b32 s8, s8, 0xf8
	v_or_b32_e32 v5, 64, v5
	s_movk_i32 s5, 0x70
	s_sub_i32 s6, s6, s8
	v_and_or_b32 v3, v5, s5, v3
	s_movk_i32 s5, 0x60
	s_lshl_b32 s7, s7, 3
	s_sext_i32_i16 s9, s1
	s_sext_i32_i8 s6, s6
	v_and_or_b32 v4, v5, s5, v4
	s_lshr_b32 s5, s4, 6
	s_add_i32 s40, s7, s6
	s_ashr_i32 s6, s9, 3
	s_lshr_b32 s0, s4, 8
	s_lshl_b32 s26, s5, 10
	s_lshr_b32 s1, s9, 3
	s_mul_hi_i32 s7, s6, 0x160000
	s_mul_i32 s6, s6, 0x160000
	v_mul_u32_u24_e32 v13, 0xb00, v3
	s_add_u32 s18, s24, s6
	v_or_b32_e32 v3, v13, v2
	s_addc_u32 s19, s25, s7
	s_add_i32 s27, s26, 0
	v_mul_u32_u24_e32 v12, 0xb00, v6
	v_lshlrev_b32_e32 v132, 1, v3
	v_mul_u32_u24_e32 v3, 0xb00, v4
	s_add_i32 m0, s27, 0x10000
	v_or_b32_e32 v6, v2, v12
	v_or_b32_e32 v2, v3, v2
	global_load_lds_dwordx4 v130, s[18:19]
	s_add_i32 m0, s27, 0x12000
	v_lshlrev_b32_e32 v134, 1, v2
	s_add_u32 s6, s18, 0xb0000
	global_load_lds_dwordx4 v134, s[18:19]
	s_addc_u32 s7, s19, 0
	s_add_i32 m0, s27, 0x14000
	s_mul_i32 s10, s40, 0x160000
	global_load_lds_dwordx4 v130, s[6:7]
	s_add_i32 m0, s27, 0x16000
	s_mul_hi_i32 s8, s40, 0x160000
	s_add_u32 s16, s22, s10
	s_addc_u32 s17, s23, s8
	s_add_i32 s28, s27, 0x2000
	v_lshlrev_b32_e32 v128, 1, v6
	global_load_lds_dwordx4 v134, s[6:7]
	s_mov_b32 m0, s27
	s_add_u32 s6, s16, 0xb0000
	global_load_lds_dwordx4 v128, s[16:17]
	s_mov_b32 m0, s28
	s_addc_u32 s7, s17, 0
	s_add_i32 s29, s27, 0x4000
	global_load_lds_dwordx4 v132, s[16:17]
	s_mov_b32 m0, s29
	s_add_i32 s30, s27, 0x6000
	global_load_lds_dwordx4 v128, s[6:7]
	s_mov_b32 m0, s30
	v_mov_b32_e32 v131, 0
	global_load_lds_dwordx4 v132, s[6:7]
	v_mov_b32_e32 v135, v131
	v_mov_b32_e32 v129, v131
	v_mov_b32_e32 v133, v131
	s_cmp_eq_u32 s0, 1
	s_mov_b32 s31, 0
	v_lshl_add_u64 v[8:9], s[18:19], 0, v[130:131]
	v_lshl_add_u64 v[6:7], s[18:19], 0, v[134:135]
	v_lshl_add_u64 v[2:3], s[16:17], 0, v[128:129]
	s_cselect_b64 s[6:7], -1, 0
	s_cmp_lg_u32 s0, 1
	v_lshl_add_u64 v[4:5], s[16:17], 0, v[132:133]
	s_cbranch_scc1 .LBB0_1590
	s_setprio 1
	s_barrier

.LBB0_1604:
	ds_read_b128 v[144:147], v155
	ds_read_b128 v[148:151], v155 offset:1024
	ds_read_b128 v[158:161], v155 offset:2048
	ds_read_b128 v[162:165], v155 offset:3072
	ds_read_b128 v[166:169], v156
	ds_read_b128 v[170:173], v156 offset:1024
	ds_read_b128 v[174:177], v156 offset:2048
	ds_read_b128 v[178:181], v156 offset:3072
	s_add_u32 s18, s16, 0xfff50080
	s_addc_u32 s19, s17, -1
	s_cmp_eq_u32 s44, 40
	s_cselect_b32 s21, s5, s19
	s_cselect_b32 s20, s4, s18
	s_cselect_b32 s19, s15, s43
	s_cselect_b32 s18, s14, s42
	v_lshl_add_u64 v[214:215], s[16:17], 0, v[136:137]
	s_add_i32 m0, s27, 0xc000
	ds_read_b128 v[182:185], v157
	ds_read_b128 v[186:189], v157 offset:1024
	ds_read_b128 v[190:193], v157 offset:2048
	ds_read_b128 v[194:197], v157 offset:3072
	ds_read_b128 v[198:201], v157 offset:4096
	ds_read_b128 v[202:205], v157 offset:5120
	ds_read_b128 v[206:209], v157 offset:6144
	ds_read_b128 v[210:213], v157 offset:7168
	global_load_lds_dwordx4 v[214:215], off
	v_lshl_add_u64 v[214:215], s[16:17], 0, v[138:139]
	s_add_i32 m0, s27, 0xe000
	s_nop 0
	global_load_lds_dwordx4 v[214:215], off
	s_waitcnt vmcnt(8)
	s_waitcnt lgkmcnt(0)
	s_barrier
	s_waitcnt lgkmcnt(0)
	v_mfma_f32_16x16x32_bf16 v[124:127], v[144:147], v[182:185], v[124:127]
	v_mfma_f32_16x16x32_bf16 v[120:123], v[158:161], v[182:185], v[120:123]
	v_mfma_f32_16x16x32_bf16 v[108:111], v[144:147], v[190:193], v[108:111]
	v_mfma_f32_16x16x32_bf16 v[104:107], v[158:161], v[190:193], v[104:107]
	v_mfma_f32_16x16x32_bf16 v[96:99], v[144:147], v[198:201], v[96:99]
	v_mfma_f32_16x16x32_bf16 v[88:91], v[158:161], v[198:201], v[88:91]
	v_mfma_f32_16x16x32_bf16 v[80:83], v[144:147], v[206:209], v[80:83]
	v_mfma_f32_16x16x32_bf16 v[72:75], v[158:161], v[206:209], v[72:75]
	v_mfma_f32_16x16x32_bf16 v[124:127], v[148:151], v[186:189], v[124:127]
	v_mfma_f32_16x16x32_bf16 v[120:123], v[162:165], v[186:189], v[120:123]
	v_mfma_f32_16x16x32_bf16 v[108:111], v[148:151], v[194:197], v[108:111]
	v_mfma_f32_16x16x32_bf16 v[104:107], v[162:165], v[194:197], v[104:107]
	v_mfma_f32_16x16x32_bf16 v[96:99], v[148:151], v[202:205], v[96:99]
	v_mfma_f32_16x16x32_bf16 v[88:91], v[162:165], v[202:205], v[88:91]
	v_mfma_f32_16x16x32_bf16 v[80:83], v[148:151], v[210:213], v[80:83]
	v_mfma_f32_16x16x32_bf16 v[72:75], v[162:165], v[210:213], v[72:75]
	v_mfma_f32_16x16x32_bf16 v[116:119], v[166:169], v[182:185], v[116:119]
	v_mfma_f32_16x16x32_bf16 v[112:115], v[174:177], v[182:185], v[112:115]
	v_mfma_f32_16x16x32_bf16 v[100:103], v[166:169], v[190:193], v[100:103]
	v_mfma_f32_16x16x32_bf16 v[92:95], v[174:177], v[190:193], v[92:95]
	v_mfma_f32_16x16x32_bf16 v[84:87], v[166:169], v[198:201], v[84:87]
	v_mfma_f32_16x16x32_bf16 v[76:79], v[174:177], v[198:201], v[76:79]
	v_mfma_f32_16x16x32_bf16 v[68:71], v[166:169], v[206:209], v[68:71]
	v_mfma_f32_16x16x32_bf16 v[64:67], v[174:177], v[206:209], v[64:67]
	v_mfma_f32_16x16x32_bf16 v[116:119], v[170:173], v[186:189], v[116:119]
	v_mfma_f32_16x16x32_bf16 v[112:115], v[178:181], v[186:189], v[112:115]
	v_mfma_f32_16x16x32_bf16 v[100:103], v[170:173], v[194:197], v[100:103]
	v_mfma_f32_16x16x32_bf16 v[92:95], v[178:181], v[194:197], v[92:95]
	v_mfma_f32_16x16x32_bf16 v[84:87], v[170:173], v[202:205], v[84:87]
	v_mfma_f32_16x16x32_bf16 v[76:79], v[178:181], v[202:205], v[76:79]
	v_mfma_f32_16x16x32_bf16 v[68:71], v[170:173], v[210:213], v[68:71]
	v_mfma_f32_16x16x32_bf16 v[64:67], v[178:181], v[210:213], v[64:67]
	s_barrier
	s_add_i32 s45, s36, s26
	v_lshl_add_u64 v[214:215], s[18:19], 0, v[130:131]
	s_mov_b32 m0, s45
	ds_read_b128 v[182:185], v157 offset:16384
	ds_read_b128 v[186:189], v157 offset:17408
	ds_read_b128 v[190:193], v157 offset:18432
	ds_read_b128 v[194:197], v157 offset:19456
	ds_read_b128 v[198:201], v157 offset:20480
	ds_read_b128 v[202:205], v157 offset:21504
	ds_read_b128 v[206:209], v157 offset:22528
	ds_read_b128 v[210:213], v157 offset:23552
	global_load_lds_dwordx4 v[214:215], off
	s_add_i32 m0, s45, 0x2000
	s_add_u32 s46, s18, 0xb0000
	v_lshl_add_u64 v[216:217], s[18:19], 0, v[134:135]
	s_addc_u32 s47, s19, 0
	s_add_i32 s45, s37, s26
	global_load_lds_dwordx4 v[216:217], off
	v_lshl_add_u64 v[218:219], s[46:47], 0, v[130:131]
	s_mov_b32 m0, s45
	v_lshl_add_u64 v[220:221], s[20:21], 0, v[132:133]
	global_load_lds_dwordx4 v[218:219], off
	v_lshl_add_u64 v[218:219], s[46:47], 0, v[134:135]
	s_add_i32 m0, s45, 0x2000
	s_nop 0
	global_load_lds_dwordx4 v[218:219], off
	v_lshl_add_u64 v[218:219], s[20:21], 0, v[128:129]
	s_mov_b32 m0, s27
	s_nop 0
	global_load_lds_dwordx4 v[218:219], off
	s_mov_b32 m0, s28
	s_nop 0
	global_load_lds_dwordx4 v[220:221], off
	s_waitcnt vmcnt(8)
	s_waitcnt lgkmcnt(0)
	s_barrier
	s_waitcnt lgkmcnt(0)
	v_mfma_f32_16x16x32_bf16 v[60:63], v[144:147], v[182:185], v[60:63]
	v_mfma_f32_16x16x32_bf16 v[56:59], v[158:161], v[182:185], v[56:59]
	v_mfma_f32_16x16x32_bf16 v[48:51], v[144:147], v[190:193], v[48:51]
	v_mfma_f32_16x16x32_bf16 v[40:43], v[158:161], v[190:193], v[40:43]
	v_mfma_f32_16x16x32_bf16 v[32:35], v[144:147], v[198:201], v[32:35]
	v_mfma_f32_16x16x32_bf16 v[24:27], v[158:161], v[198:201], v[24:27]
	v_mfma_f32_16x16x32_bf16 v[16:19], v[144:147], v[206:209], v[16:19]
	v_mfma_f32_16x16x32_bf16 v[8:11], v[158:161], v[206:209], v[8:11]
	v_mfma_f32_16x16x32_bf16 v[60:63], v[148:151], v[186:189], v[60:63]
	v_mfma_f32_16x16x32_bf16 v[56:59], v[162:165], v[186:189], v[56:59]
	v_mfma_f32_16x16x32_bf16 v[48:51], v[148:151], v[194:197], v[48:51]
	v_mfma_f32_16x16x32_bf16 v[40:43], v[162:165], v[194:197], v[40:43]
	v_mfma_f32_16x16x32_bf16 v[32:35], v[148:151], v[202:205], v[32:35]
	v_mfma_f32_16x16x32_bf16 v[24:27], v[162:165], v[202:205], v[24:27]
	v_mfma_f32_16x16x32_bf16 v[16:19], v[148:151], v[210:213], v[16:19]
	v_mfma_f32_16x16x32_bf16 v[8:11], v[162:165], v[210:213], v[8:11]
	v_mfma_f32_16x16x32_bf16 v[52:55], v[166:169], v[182:185], v[52:55]
	v_mfma_f32_16x16x32_bf16 v[44:47], v[174:177], v[182:185], v[44:47]
	v_mfma_f32_16x16x32_bf16 v[36:39], v[166:169], v[190:193], v[36:39]
	v_mfma_f32_16x16x32_bf16 v[28:31], v[174:177], v[190:193], v[28:31]
	v_mfma_f32_16x16x32_bf16 v[20:23], v[166:169], v[198:201], v[20:23]
	v_mfma_f32_16x16x32_bf16 v[12:15], v[174:177], v[198:201], v[12:15]
	v_mfma_f32_16x16x32_bf16 v[4:7], v[166:169], v[206:209], v[4:7]
	v_mfma_f32_16x16x32_bf16 v[0:3], v[174:177], v[206:209], v[0:3]
	v_mfma_f32_16x16x32_bf16 v[52:55], v[170:173], v[186:189], v[52:55]
	v_mfma_f32_16x16x32_bf16 v[44:47], v[178:181], v[186:189], v[44:47]
	v_mfma_f32_16x16x32_bf16 v[36:39], v[170:173], v[194:197], v[36:39]
	v_mfma_f32_16x16x32_bf16 v[28:31], v[178:181], v[194:197], v[28:31]
	v_mfma_f32_16x16x32_bf16 v[20:23], v[170:173], v[202:205], v[20:23]
	v_mfma_f32_16x16x32_bf16 v[12:15], v[178:181], v[202:205], v[12:15]
	v_mfma_f32_16x16x32_bf16 v[4:7], v[170:173], v[210:213], v[4:7]
	v_mfma_f32_16x16x32_bf16 v[0:3], v[178:181], v[210:213], v[0:3]
	s_barrier
	s_add_i32 s45, 0, 0x18000
	s_add_i32 s46, 0, 0x1c000
	v_add_u32_e32 v162, s45, v153
	v_add_u32_e32 v178, s46, v153
	ds_read_b128 v[144:147], v162
	ds_read_b128 v[148:151], v162 offset:1024
	ds_read_b128 v[158:161], v162 offset:2048
	ds_read_b128 v[162:165], v162 offset:3072
	ds_read_b128 v[166:169], v178
	ds_read_b128 v[170:173], v178 offset:1024
	ds_read_b128 v[174:177], v178 offset:2048
	ds_read_b128 v[178:181], v178 offset:3072
	s_add_u32 s20, s20, 0xb0000
	s_addc_u32 s21, s21, 0
	s_mov_b32 m0, s29
	v_lshl_add_u64 v[222:223], s[20:21], 0, v[128:129]
	ds_read_b128 v[182:185], v157 offset:32768
	ds_read_b128 v[186:189], v157 offset:33792
	ds_read_b128 v[190:193], v157 offset:34816
	ds_read_b128 v[194:197], v157 offset:35840
	ds_read_b128 v[198:201], v157 offset:36864
	ds_read_b128 v[202:205], v157 offset:37888
	ds_read_b128 v[206:209], v157 offset:38912
	ds_read_b128 v[210:213], v157 offset:39936
	global_load_lds_dwordx4 v[222:223], off
	v_lshl_add_u64 v[222:223], s[20:21], 0, v[132:133]
	s_mov_b32 m0, s30
	s_nop 0
	global_load_lds_dwordx4 v[222:223], off
	s_waitcnt vmcnt(8)
	s_waitcnt lgkmcnt(0)
	s_barrier
	s_waitcnt lgkmcnt(0)
	v_mfma_f32_16x16x32_bf16 v[124:127], v[144:147], v[182:185], v[124:127]
	v_mfma_f32_16x16x32_bf16 v[120:123], v[158:161], v[182:185], v[120:123]
	v_mfma_f32_16x16x32_bf16 v[108:111], v[144:147], v[190:193], v[108:111]
	v_mfma_f32_16x16x32_bf16 v[104:107], v[158:161], v[190:193], v[104:107]
	v_mfma_f32_16x16x32_bf16 v[96:99], v[144:147], v[198:201], v[96:99]
	v_mfma_f32_16x16x32_bf16 v[88:91], v[158:161], v[198:201], v[88:91]
	v_mfma_f32_16x16x32_bf16 v[80:83], v[144:147], v[206:209], v[80:83]
	v_mfma_f32_16x16x32_bf16 v[72:75], v[158:161], v[206:209], v[72:75]
	v_mfma_f32_16x16x32_bf16 v[124:127], v[148:151], v[186:189], v[124:127]
	v_mfma_f32_16x16x32_bf16 v[120:123], v[162:165], v[186:189], v[120:123]
	v_mfma_f32_16x16x32_bf16 v[108:111], v[148:151], v[194:197], v[108:111]
	v_mfma_f32_16x16x32_bf16 v[104:107], v[162:165], v[194:197], v[104:107]
	v_mfma_f32_16x16x32_bf16 v[96:99], v[148:151], v[202:205], v[96:99]
	v_mfma_f32_16x16x32_bf16 v[88:91], v[162:165], v[202:205], v[88:91]
	v_mfma_f32_16x16x32_bf16 v[80:83], v[148:151], v[210:213], v[80:83]
	v_mfma_f32_16x16x32_bf16 v[72:75], v[162:165], v[210:213], v[72:75]
	v_mfma_f32_16x16x32_bf16 v[116:119], v[166:169], v[182:185], v[116:119]
	v_mfma_f32_16x16x32_bf16 v[112:115], v[174:177], v[182:185], v[112:115]
	v_mfma_f32_16x16x32_bf16 v[100:103], v[166:169], v[190:193], v[100:103]
	v_mfma_f32_16x16x32_bf16 v[92:95], v[174:177], v[190:193], v[92:95]
	v_mfma_f32_16x16x32_bf16 v[84:87], v[166:169], v[198:201], v[84:87]
	v_mfma_f32_16x16x32_bf16 v[76:79], v[174:177], v[198:201], v[76:79]
	v_mfma_f32_16x16x32_bf16 v[68:71], v[166:169], v[206:209], v[68:71]
	v_mfma_f32_16x16x32_bf16 v[64:67], v[174:177], v[206:209], v[64:67]
	v_mfma_f32_16x16x32_bf16 v[116:119], v[170:173], v[186:189], v[116:119]
	v_mfma_f32_16x16x32_bf16 v[112:115], v[178:181], v[186:189], v[112:115]
	v_mfma_f32_16x16x32_bf16 v[100:103], v[170:173], v[194:197], v[100:103]
	v_mfma_f32_16x16x32_bf16 v[92:95], v[178:181], v[194:197], v[92:95]
	v_mfma_f32_16x16x32_bf16 v[84:87], v[170:173], v[202:205], v[84:87]
	v_mfma_f32_16x16x32_bf16 v[76:79], v[178:181], v[202:205], v[76:79]
	v_mfma_f32_16x16x32_bf16 v[68:71], v[170:173], v[210:213], v[68:71]
	v_mfma_f32_16x16x32_bf16 v[64:67], v[178:181], v[210:213], v[64:67]
	s_barrier
	s_add_i32 s20, s45, s26
	v_lshl_add_u64 v[214:215], v[214:215], 0, s[10:11]
	s_mov_b32 m0, s20
	ds_read_b128 v[182:185], v157 offset:49152
	ds_read_b128 v[186:189], v157 offset:50176
	ds_read_b128 v[190:193], v157 offset:51200
	ds_read_b128 v[194:197], v157 offset:52224
	ds_read_b128 v[198:201], v157 offset:53248
	ds_read_b128 v[202:205], v157 offset:54272
	ds_read_b128 v[206:209], v157 offset:55296
	ds_read_b128 v[210:213], v157 offset:56320
	global_load_lds_dwordx4 v[214:215], off
	s_add_i32 m0, s20, 0x2000
	s_add_u32 s18, s18, 0xb0080
	v_lshl_add_u64 v[214:215], v[216:217], 0, s[10:11]
	s_addc_u32 s19, s19, 0
	s_add_i32 s20, s46, s26
	global_load_lds_dwordx4 v[214:215], off
	v_lshl_add_u64 v[214:215], s[18:19], 0, v[130:131]
	s_mov_b32 m0, s20
	s_nop 0
	global_load_lds_dwordx4 v[214:215], off
	v_lshl_add_u64 v[214:215], s[18:19], 0, v[134:135]
	s_add_i32 m0, s20, 0x2000
	s_nop 0
	global_load_lds_dwordx4 v[214:215], off
	v_lshl_add_u64 v[214:215], v[218:219], 0, s[10:11]
	s_mov_b32 m0, s33
	s_nop 0
	global_load_lds_dwordx4 v[214:215], off
	v_lshl_add_u64 v[214:215], v[220:221], 0, s[10:11]
	s_mov_b32 m0, s34
	s_nop 0
	global_load_lds_dwordx4 v[214:215], off
	s_waitcnt vmcnt(8)
	s_waitcnt lgkmcnt(0)
	s_barrier
	s_waitcnt lgkmcnt(0)
	v_mfma_f32_16x16x32_bf16 v[60:63], v[144:147], v[182:185], v[60:63]
	v_mfma_f32_16x16x32_bf16 v[56:59], v[158:161], v[182:185], v[56:59]
	v_mfma_f32_16x16x32_bf16 v[48:51], v[144:147], v[190:193], v[48:51]
	v_mfma_f32_16x16x32_bf16 v[40:43], v[158:161], v[190:193], v[40:43]
	v_mfma_f32_16x16x32_bf16 v[32:35], v[144:147], v[198:201], v[32:35]
	v_mfma_f32_16x16x32_bf16 v[24:27], v[158:161], v[198:201], v[24:27]
	v_mfma_f32_16x16x32_bf16 v[16:19], v[144:147], v[206:209], v[16:19]
	v_mfma_f32_16x16x32_bf16 v[8:11], v[158:161], v[206:209], v[8:11]
	v_mfma_f32_16x16x32_bf16 v[60:63], v[148:151], v[186:189], v[60:63]
	v_mfma_f32_16x16x32_bf16 v[56:59], v[162:165], v[186:189], v[56:59]
	v_mfma_f32_16x16x32_bf16 v[48:51], v[148:151], v[194:197], v[48:51]
	v_mfma_f32_16x16x32_bf16 v[40:43], v[162:165], v[194:197], v[40:43]
	v_mfma_f32_16x16x32_bf16 v[32:35], v[148:151], v[202:205], v[32:35]
	v_mfma_f32_16x16x32_bf16 v[24:27], v[162:165], v[202:205], v[24:27]
	v_mfma_f32_16x16x32_bf16 v[16:19], v[148:151], v[210:213], v[16:19]
	v_mfma_f32_16x16x32_bf16 v[8:11], v[162:165], v[210:213], v[8:11]
	v_mfma_f32_16x16x32_bf16 v[52:55], v[166:169], v[182:185], v[52:55]
	v_mfma_f32_16x16x32_bf16 v[44:47], v[174:177], v[182:185], v[44:47]
	v_mfma_f32_16x16x32_bf16 v[36:39], v[166:169], v[190:193], v[36:39]
	v_mfma_f32_16x16x32_bf16 v[28:31], v[174:177], v[190:193], v[28:31]
	v_mfma_f32_16x16x32_bf16 v[20:23], v[166:169], v[198:201], v[20:23]
	v_mfma_f32_16x16x32_bf16 v[12:15], v[174:177], v[198:201], v[12:15]
	v_mfma_f32_16x16x32_bf16 v[4:7], v[166:169], v[206:209], v[4:7]
	v_mfma_f32_16x16x32_bf16 v[0:3], v[174:177], v[206:209], v[0:3]
	v_mfma_f32_16x16x32_bf16 v[52:55], v[170:173], v[186:189], v[52:55]
	v_mfma_f32_16x16x32_bf16 v[44:47], v[178:181], v[186:189], v[44:47]
	v_mfma_f32_16x16x32_bf16 v[36:39], v[170:173], v[194:197], v[36:39]
	v_mfma_f32_16x16x32_bf16 v[28:31], v[178:181], v[194:197], v[28:31]
	v_mfma_f32_16x16x32_bf16 v[20:23], v[170:173], v[202:205], v[20:23]
	v_mfma_f32_16x16x32_bf16 v[12:15], v[178:181], v[202:205], v[12:15]
	v_mfma_f32_16x16x32_bf16 v[4:7], v[170:173], v[210:213], v[4:7]
	v_mfma_f32_16x16x32_bf16 v[0:3], v[178:181], v[210:213], v[0:3]
	s_barrier
	s_add_i32 s44, s44, 2
	s_add_u32 s16, s16, 0x100
	s_addc_u32 s17, s17, 0
	s_add_u32 s42, s42, 0x100
	s_addc_u32 s43, s43, 0
	s_cmp_gt_u32 s44, 41
	s_cbranch_scc0 .LBB0_1604
	s_and_b64 vcc, exec, s[12:13]
	s_cbranch_vccz .LBB0_1607
	s_barrier
